# up-proj epilogue: the two 8-byte activation stores of a row merged into one 16-byte store (on top of the 192-row loop change)
# baseline (speedup 1.0000x reference)
;     __device__ __forceinline__ void operator()(const f32x4 (&acc_)[2][2][4][2], const pg8::Unit& u, int wr, int wc, int fr, int fq) const {
;     ...
;             for (int eh = 0; eh < 2; ++eh) {
;                 f32x4 w[2][3], bia[2], hm1[2], hm2[2];
; #pragma unroll
;                 for (int bj = 0; bj < 2; ++bj) {
;                     const int cc = bj * DFF + ch + 4 * eh;
; #pragma unroll
;                     for (int j = 0; j < 3; ++j) w[bj][j] = *(const LAS f32x4*)(cwl + (2 * j + bj) * 128 + 4 * eh);
;                     bia[bj] = *(const LAS f32x4*)(cwl + (6 + bj) * 128 + 4 * eh);
;                     if (!prompt) { const float* ps = past + (size_t)((blk0 - MP) >> 6) * 2 * DFF2 + cc; hm2[bj] = *(const f32x4*)ps; hm1[bj] = *(const f32x4*)(ps + DFF2); }
;                     else if (ai == 0 && wr == 0) { hm1[bj] = (f32x4){0.f, 0.f, 0.f, 0.f}; hm2[bj] = hm1[bj]; }
;                     else { const int pb = ai * 2 + wr - 1; const LAS float* s = hl + (((pb * 4 + wc) * 2 + 0) * 4 + fq) * 16 + bj * 8 + 4 * eh; hm2[bj] = *(const LAS f32x4*)s; hm1[bj] = *(const LAS f32x4*)(s + 64); }
;                 }
;                 u32x2 pk[4]; f32x4 pr1[2], pr2[2];
; #pragma unroll
;                 for (int bj = 0; bj < 2; ++bj)
; #pragma unroll
;                     for (int e = 0; e < 4; ++e) { pr1[bj][e] = hm1[bj][e]; pr2[bj][e] = (fr == 0) ? hm2[bj][e] : hm1[bj][e]; }
; #pragma unroll
;                 for (int m = 0; m < 4; ++m) {
;                     f32x4 c[2];
; #pragma unroll
;                     for (int bj = 0; bj < 2; ++bj) {
;                         const f32x4 h0 = acc[ai][bj][m][eh]; f32x4 p1, p2;
; #pragma unroll
;                         for (int e = 0; e < 4; ++e) {
;                             const float r1 = dpp_ror1(h0[e]), r2 = dpp_ror2(h0[e]);
;                             p1[e] = (fr >= 1) ? r1 : pr1[bj][e]; p2[e] = (fr >= 2) ? r2 : pr2[bj][e];
;                             pr1[bj][e] = r1; pr2[bj][e] = r2;
;                         }
;                         c[bj] = bia[bj] + w[bj][0] * p2 + w[bj][1] * p1 + w[bj][2] * h0;
;                     }
;                     f32x4 o;
; #pragma unroll
;                     for (int e = 0; e < 4; ++e) o[e] = silu_f(c[0][e]) * c[1][e];
;                     pk[m].x = cvt_pk_bf16(o[0], o[1]); pk[m].y = cvt_pk_bf16(o[2], o[3]);
;                 }
; #pragma unroll
.LBB0_1828:
	v_mov_b32_e32 v212, v199
	v_cmp_eq_u32_e64 s[10:11], 0, v210
	v_pk_mul_f32 v[206:207], v[102:103], v[198:199] op_sel_hi:[1,0]
	v_pk_mul_f32 v[102:103], v[100:101], v[212:213] op_sel_hi:[1,0]
	s_waitcnt vmcnt(0) lgkmcnt(0)
	v_cndmask_b32_e64 v101, v162, v166, s[10:11]
	v_cndmask_b32_e64 v166, v164, v168, s[10:11]
	v_cndmask_b32_e64 v168, v170, v174, s[10:11]
	v_cndmask_b32_e64 v174, v172, v176, s[10:11]
	v_mov_b32_dpp v176, v126 row_ror:1 row_mask:0xf bank_mask:0xf bound_ctrl:1
	v_cmp_lt_u32_e64 s[12:13], 1, v210
	v_mov_b32_dpp v214, v128 row_ror:1 row_mask:0xf bank_mask:0xf bound_ctrl:1
	v_mov_b32_dpp v215, v128 row_ror:2 row_mask:0xf bank_mask:0xf bound_ctrl:1
	v_pk_mul_f32 v[204:205], v[104:105], v[198:199] op_sel_hi:[1,0]
	v_pk_mul_f32 v[104:105], v[108:109], v[212:213] op_sel_hi:[1,0]
	v_pk_mul_f32 v[106:107], v[106:107], v[212:213] op_sel_hi:[1,0]
	v_pk_mul_f32 v[98:99], v[98:99], v[212:213] op_sel_hi:[1,0]
	v_cndmask_b32_e64 v109, v163, v167, s[10:11]
	v_cndmask_b32_e64 v167, v165, v169, s[10:11]
	v_cndmask_b32_e64 v169, v171, v175, s[10:11]
	v_cndmask_b32_e64 v175, v173, v177, s[10:11]
	v_mov_b32_dpp v177, v126 row_ror:2 row_mask:0xf bank_mask:0xf bound_ctrl:1
	v_cndmask_b32_e64 v100, v176, v162, s[10:11]
	v_mov_b32_dpp v212, v127 row_ror:1 row_mask:0xf bank_mask:0xf bound_ctrl:1
	v_mov_b32_dpp v213, v127 row_ror:2 row_mask:0xf bank_mask:0xf bound_ctrl:1
	v_cndmask_b32_e64 v162, v214, v164, s[10:11]
	v_cndmask_b32_e64 v164, v166, v215, s[12:13]
	v_mov_b32_dpp v166, v129 row_ror:1 row_mask:0xf bank_mask:0xf bound_ctrl:1
	v_mov_b32_dpp v216, v129 row_ror:2 row_mask:0xf bank_mask:0xf bound_ctrl:1
	v_cndmask_b32_e64 v108, v101, v177, s[12:13]
	v_cndmask_b32_e64 v101, v212, v163, s[10:11]
	v_cndmask_b32_e64 v109, v109, v213, s[12:13]
	v_cndmask_b32_e64 v163, v166, v165, s[10:11]
	v_cndmask_b32_e64 v165, v167, v216, s[12:13]
	v_pk_fma_f32 v[164:165], v[140:141], v[164:165], v[144:145]
	v_pk_fma_f32 v[108:109], v[138:139], v[108:109], v[142:143]
	v_mov_b32_dpp v217, v122 row_ror:2 row_mask:0xf bank_mask:0xf bound_ctrl:1
	v_pk_fma_f32 v[100:101], v[134:135], v[100:101], v[108:109]
	v_pk_fma_f32 v[108:109], v[136:137], v[162:163], v[164:165]
	v_mov_b32_dpp v167, v122 row_ror:1 row_mask:0xf bank_mask:0xf bound_ctrl:1
	v_pk_fma_f32 v[108:109], v[128:129], v[132:133], v[108:109]
	v_cndmask_b32_e64 v128, v168, v217, s[12:13]
	v_mov_b32_dpp v168, v123 row_ror:1 row_mask:0xf bank_mask:0xf bound_ctrl:1
	v_pk_fma_f32 v[100:101], v[126:127], v[130:131], v[100:101]
	v_cndmask_b32_e64 v126, v167, v170, s[10:11]
	v_mov_b32_dpp v170, v123 row_ror:2 row_mask:0xf bank_mask:0xf bound_ctrl:1
	v_cndmask_b32_e64 v127, v168, v171, s[10:11]
	v_mov_b32_dpp v171, v124 row_ror:2 row_mask:0xf bank_mask:0xf bound_ctrl:1
	v_cndmask_b32_e64 v129, v169, v170, s[12:13]
	v_mov_b32_dpp v169, v124 row_ror:1 row_mask:0xf bank_mask:0xf bound_ctrl:1
	v_cndmask_b32_e64 v164, v174, v171, s[12:13]
	v_mov_b32_dpp v174, v125 row_ror:2 row_mask:0xf bank_mask:0xf bound_ctrl:1
	v_cndmask_b32_e64 v162, v169, v172, s[10:11]
	v_mov_b32_dpp v172, v125 row_ror:1 row_mask:0xf bank_mask:0xf bound_ctrl:1
	v_cndmask_b32_e64 v165, v175, v174, s[12:13]
	v_cndmask_b32_e64 v163, v172, v173, s[10:11]
	v_pk_fma_f32 v[164:165], v[156:157], v[164:165], v[160:161]
	v_pk_fma_f32 v[128:129], v[154:155], v[128:129], v[158:159]
	v_pk_mul_f32 v[112:113], v[112:113], v[198:199] op_sel_hi:[1,0]
	v_pk_fma_f32 v[126:127], v[150:151], v[126:127], v[128:129]
	v_pk_fma_f32 v[128:129], v[152:153], v[162:163], v[164:165]
	v_mul_f32_e32 v162, 0xbfb8aa3b, v100
	v_mul_f32_e32 v163, 0xbfb8aa3b, v101
	v_exp_f32_e32 v162, v162
	v_exp_f32_e32 v163, v163
	v_pk_fma_f32 v[124:125], v[124:125], v[148:149], v[128:129]
	v_pk_mul_f32 v[110:111], v[110:111], v[198:199] op_sel_hi:[1,0]
	v_add_f32_e32 v128, 1.0, v162
	v_add_f32_e32 v129, 1.0, v163
	v_mul_f32_e32 v162, 0xbfb8aa3b, v108
	v_mul_f32_e32 v163, 0xbfb8aa3b, v109
	v_exp_f32_e32 v162, v162
	v_exp_f32_e32 v163, v163
	v_rcp_f32_e32 v128, v128
	v_rcp_f32_e32 v129, v129
	v_add_f32_e32 v162, 1.0, v162
	v_add_f32_e32 v163, 1.0, v163
	v_rcp_f32_e32 v162, v162
	v_rcp_f32_e32 v163, v163
	v_pk_fma_f32 v[122:123], v[122:123], v[146:147], v[126:127]
	v_pk_mul_f32 v[100:101], v[100:101], v[128:129]
	v_mov_b32_dpp v129, v110 row_ror:2 row_mask:0xf bank_mask:0xf bound_ctrl:1
	v_pk_mul_f32 v[108:109], v[108:109], v[162:163]
	v_mov_b32_dpp v163, v111 row_ror:2 row_mask:0xf bank_mask:0xf bound_ctrl:1
	v_mov_b32_dpp v165, v112 row_ror:2 row_mask:0xf bank_mask:0xf bound_ctrl:1
	v_mov_b32_dpp v175, v113 row_ror:2 row_mask:0xf bank_mask:0xf bound_ctrl:1
	v_pk_mul_f32 v[100:101], v[100:101], v[122:123]
	v_pk_mul_f32 v[108:109], v[108:109], v[124:125]
	v_mov_b32_dpp v128, v110 row_ror:1 row_mask:0xf bank_mask:0xf bound_ctrl:1
	v_cndmask_b32_e64 v122, v177, v129, s[12:13]
	v_mov_b32_dpp v162, v111 row_ror:1 row_mask:0xf bank_mask:0xf bound_ctrl:1
	v_cndmask_b32_e64 v123, v213, v163, s[12:13]
	v_mov_b32_dpp v164, v112 row_ror:1 row_mask:0xf bank_mask:0xf bound_ctrl:1
	v_cndmask_b32_e64 v126, v215, v165, s[12:13]
	v_mov_b32_dpp v173, v113 row_ror:1 row_mask:0xf bank_mask:0xf bound_ctrl:1
	v_cndmask_b32_e64 v127, v216, v175, s[12:13]
	v_cvt_pk_bf16_f32 v218, v100, v101
	v_cvt_pk_bf16_f32 v219, v108, v109
	v_cndmask_b32_e64 v108, v128, v176, s[10:11]
	v_cndmask_b32_e64 v109, v162, v212, s[10:11]
	v_cndmask_b32_e64 v124, v164, v214, s[10:11]
	v_cndmask_b32_e64 v125, v173, v166, s[10:11]
	v_pk_fma_f32 v[122:123], v[138:139], v[122:123], v[142:143]
	v_pk_fma_f32 v[126:127], v[140:141], v[126:127], v[144:145]
	v_pk_fma_f32 v[108:109], v[134:135], v[108:109], v[122:123]
; __device__ __forceinline__ unsigned cvt_pk_bf16(float lo, float hi) { const f32x2 v = {lo, hi}; unsigned r = __builtin_bit_cast(unsigned, __builtin_convertvector(v, bf16x2_t)); asm volatile("" : "+v"(r)); return r; }
; __device__ __forceinline__ float silu_f(float x) { return x * __builtin_amdgcn_rcpf(1.0f + __expf(-x)); }
; __device__ __forceinline__ float dpp_ror1(float x) { return __builtin_bit_cast(float, __builtin_amdgcn_update_dpp(0, __builtin_bit_cast(int, x), 0x121, 0xf, 0xf, true)); }
; __device__ __forceinline__ float dpp_ror2(float x) { return __builtin_bit_cast(float, __builtin_amdgcn_update_dpp(0, __builtin_bit_cast(int, x), 0x122, 0xf, 0xf, true)); }
;     __device__ __forceinline__ void operator()(const f32x4 (&acc_)[2][2][4][2], const pg8::Unit& u, int wr, int wc, int fr, int fq) const {
;     ...
;                 for (int m = 0; m < 4; ++m) {
;                     f32x4 c[2];
; #pragma unroll
;                     for (int bj = 0; bj < 2; ++bj) {
;                         const f32x4 h0 = acc[ai][bj][m][eh]; f32x4 p1, p2;
; #pragma unroll
;                         for (int e = 0; e < 4; ++e) {
;                             const float r1 = dpp_ror1(h0[e]), r2 = dpp_ror2(h0[e]);
;                             p1[e] = (fr >= 1) ? r1 : pr1[bj][e]; p2[e] = (fr >= 2) ? r2 : pr2[bj][e];
;                             pr1[bj][e] = r1; pr2[bj][e] = r2;
;                         }
;                         c[bj] = bia[bj] + w[bj][0] * p2 + w[bj][1] * p1 + w[bj][2] * h0;
;                     }
;                     f32x4 o;
; #pragma unroll
;                     for (int e = 0; e < 4; ++e) o[e] = silu_f(c[0][e]) * c[1][e];
;                     pk[m].x = cvt_pk_bf16(o[0], o[1]); pk[m].y = cvt_pk_bf16(o[2], o[3]);
;                 }
	v_pk_fma_f32 v[122:123], v[136:137], v[124:125], v[126:127]
	v_mov_b32_dpp v166, v206 row_ror:1 row_mask:0xf bank_mask:0xf bound_ctrl:1
	v_mov_b32_dpp v177, v207 row_ror:2 row_mask:0xf bank_mask:0xf bound_ctrl:1
	v_pk_fma_f32 v[108:109], v[110:111], v[130:131], v[108:109]
	v_pk_fma_f32 v[110:111], v[112:113], v[132:133], v[122:123]
	v_cndmask_b32_e64 v112, v166, v167, s[10:11]
	v_mov_b32_dpp v167, v207 row_ror:1 row_mask:0xf bank_mask:0xf bound_ctrl:1
	v_cndmask_b32_e64 v123, v170, v177, s[12:13]
	v_mov_b32_dpp v170, v204 row_ror:2 row_mask:0xf bank_mask:0xf bound_ctrl:1
	v_mov_b32_dpp v176, v206 row_ror:2 row_mask:0xf bank_mask:0xf bound_ctrl:1
	v_cndmask_b32_e64 v113, v167, v168, s[10:11]
	v_mov_b32_dpp v168, v204 row_ror:1 row_mask:0xf bank_mask:0xf bound_ctrl:1
	v_cndmask_b32_e64 v126, v171, v170, s[12:13]
	v_mov_b32_dpp v171, v205 row_ror:2 row_mask:0xf bank_mask:0xf bound_ctrl:1
	v_cndmask_b32_e64 v122, v217, v176, s[12:13]
	v_cndmask_b32_e64 v124, v168, v169, s[10:11]
	v_mov_b32_dpp v169, v205 row_ror:1 row_mask:0xf bank_mask:0xf bound_ctrl:1
	v_cndmask_b32_e64 v127, v174, v171, s[12:13]
	v_cndmask_b32_e64 v125, v169, v172, s[10:11]
	v_pk_fma_f32 v[122:123], v[154:155], v[122:123], v[158:159]
	v_pk_fma_f32 v[126:127], v[156:157], v[126:127], v[160:161]
	v_pk_fma_f32 v[112:113], v[150:151], v[112:113], v[122:123]
	v_pk_fma_f32 v[122:123], v[152:153], v[124:125], v[126:127]
	v_mul_f32_e32 v124, 0xbfb8aa3b, v108
	v_mul_f32_e32 v125, 0xbfb8aa3b, v109
	v_mul_f32_e32 v126, 0xbfb8aa3b, v110
	v_mul_f32_e32 v127, 0xbfb8aa3b, v111
	v_exp_f32_e32 v124, v124
	v_exp_f32_e32 v125, v125
	v_exp_f32_e32 v126, v126
	v_exp_f32_e32 v127, v127
	v_add_f32_e32 v124, 1.0, v124
	v_add_f32_e32 v125, 1.0, v125
	v_add_f32_e32 v126, 1.0, v126
	v_add_f32_e32 v127, 1.0, v127
	v_rcp_f32_e32 v124, v124
	v_rcp_f32_e32 v125, v125
	v_rcp_f32_e32 v126, v126
	v_rcp_f32_e32 v127, v127
	v_pk_fma_f32 v[112:113], v[206:207], v[146:147], v[112:113]
	v_pk_fma_f32 v[122:123], v[204:205], v[148:149], v[122:123]
	v_pk_mul_f32 v[108:109], v[108:109], v[124:125]
	v_pk_mul_f32 v[110:111], v[110:111], v[126:127]
	v_mov_b32_dpp v127, v106 row_ror:2 row_mask:0xf bank_mask:0xf bound_ctrl:1
	v_pk_mul_f32 v[108:109], v[108:109], v[112:113]
	v_pk_mul_f32 v[110:111], v[110:111], v[122:123]
	v_mov_b32_dpp v126, v106 row_ror:1 row_mask:0xf bank_mask:0xf bound_ctrl:1
	v_cndmask_b32_e64 v112, v129, v127, s[12:13]
	v_mov_b32_dpp v129, v107 row_ror:2 row_mask:0xf bank_mask:0xf bound_ctrl:1
	v_cvt_pk_bf16_f32 v222, v108, v109
	v_cvt_pk_bf16_f32 v223, v110, v111
	v_cndmask_b32_e64 v110, v126, v128, s[10:11]
	v_mov_b32_dpp v128, v107 row_ror:1 row_mask:0xf bank_mask:0xf bound_ctrl:1
	v_cndmask_b32_e64 v113, v163, v129, s[12:13]
	v_mov_b32_dpp v163, v104 row_ror:2 row_mask:0xf bank_mask:0xf bound_ctrl:1
	v_cndmask_b32_e64 v111, v128, v162, s[10:11]
	v_mov_b32_dpp v162, v104 row_ror:1 row_mask:0xf bank_mask:0xf bound_ctrl:1
	v_cndmask_b32_e64 v124, v165, v163, s[12:13]
	v_mov_b32_dpp v165, v105 row_ror:2 row_mask:0xf bank_mask:0xf bound_ctrl:1
	v_pk_fma_f32 v[112:113], v[138:139], v[112:113], v[142:143]
	v_cndmask_b32_e64 v122, v162, v164, s[10:11]
	v_mov_b32_dpp v164, v105 row_ror:1 row_mask:0xf bank_mask:0xf bound_ctrl:1
	v_cndmask_b32_e64 v125, v175, v165, s[12:13]
	v_pk_fma_f32 v[110:111], v[134:135], v[110:111], v[112:113]
	v_mov_b32_dpp v172, v98 row_ror:1 row_mask:0xf bank_mask:0xf bound_ctrl:1
	v_cndmask_b32_e64 v123, v164, v173, s[10:11]
	v_pk_fma_f32 v[124:125], v[140:141], v[124:125], v[144:145]
	v_pk_fma_f32 v[106:107], v[106:107], v[130:131], v[110:111]
	v_cndmask_b32_e64 v110, v172, v166, s[10:11]
	v_mov_b32_dpp v166, v99 row_ror:1 row_mask:0xf bank_mask:0xf bound_ctrl:1
	v_mov_b32_dpp v175, v102 row_ror:2 row_mask:0xf bank_mask:0xf bound_ctrl:1
	v_pk_fma_f32 v[112:113], v[136:137], v[122:123], v[124:125]
	v_mov_b32_dpp v173, v98 row_ror:2 row_mask:0xf bank_mask:0xf bound_ctrl:1
	v_mov_b32_dpp v174, v99 row_ror:2 row_mask:0xf bank_mask:0xf bound_ctrl:1
	v_cndmask_b32_e64 v111, v166, v167, s[10:11]
	v_mov_b32_dpp v167, v102 row_ror:1 row_mask:0xf bank_mask:0xf bound_ctrl:1
	v_cndmask_b32_e64 v124, v170, v175, s[12:13]
	v_mov_b32_dpp v170, v103 row_ror:2 row_mask:0xf bank_mask:0xf bound_ctrl:1
	v_pk_fma_f32 v[104:105], v[104:105], v[132:133], v[112:113]
	v_cndmask_b32_e64 v112, v176, v173, s[12:13]
	v_cndmask_b32_e64 v113, v177, v174, s[12:13]
	v_cndmask_b32_e64 v122, v167, v168, s[10:11]
	v_mov_b32_dpp v168, v103 row_ror:1 row_mask:0xf bank_mask:0xf bound_ctrl:1
	v_cndmask_b32_e64 v125, v171, v170, s[12:13]
	v_cndmask_b32_e64 v123, v168, v169, s[10:11]
	v_pk_fma_f32 v[124:125], v[156:157], v[124:125], v[160:161]
	v_pk_fma_f32 v[112:113], v[154:155], v[112:113], v[158:159]
	v_lshl_add_u64 v[196:197], v[194:195], 1, s[34:35]
	v_pk_fma_f32 v[110:111], v[150:151], v[110:111], v[112:113]
	v_pk_fma_f32 v[112:113], v[152:153], v[122:123], v[124:125]
	v_mul_f32_e32 v122, 0xbfb8aa3b, v106
	v_mul_f32_e32 v123, 0xbfb8aa3b, v107
	v_exp_f32_e32 v122, v122
	v_exp_f32_e32 v123, v123
; #define LAS __attribute__((address_space(3)))
; __device__ __forceinline__ unsigned cvt_pk_bf16(float lo, float hi) { const f32x2 v = {lo, hi}; unsigned r = __builtin_bit_cast(unsigned, __builtin_convertvector(v, bf16x2_t)); asm volatile("" : "+v"(r)); return r; }
; __device__ __forceinline__ float silu_f(float x) { return x * __builtin_amdgcn_rcpf(1.0f + __expf(-x)); }
;     __device__ __forceinline__ void operator()(const f32x4 (&acc_)[2][2][4][2], const pg8::Unit& u, int wr, int wc, int fr, int fq) const {
;     ...
;                     const int cc = bj * DFF + ch + 4 * eh;
; #pragma unroll
;                     for (int j = 0; j < 3; ++j) w[bj][j] = *(const LAS f32x4*)(cwl + (2 * j + bj) * 128 + 4 * eh);
;                     bia[bj] = *(const LAS f32x4*)(cwl + (6 + bj) * 128 + 4 * eh);
;                     if (!prompt) { const float* ps = past + (size_t)((blk0 - MP) >> 6) * 2 * DFF2 + cc; hm2[bj] = *(const f32x4*)ps; hm1[bj] = *(const f32x4*)(ps + DFF2); }
;                     else if (ai == 0 && wr == 0) { hm1[bj] = (f32x4){0.f, 0.f, 0.f, 0.f}; hm2[bj] = hm1[bj]; }
;                     else { const int pb = ai * 2 + wr - 1; const LAS float* s = hl + (((pb * 4 + wc) * 2 + 0) * 4 + fq) * 16 + bj * 8 + 4 * eh; hm2[bj] = *(const LAS f32x4*)s; hm1[bj] = *(const LAS f32x4*)(s + 64); }
;     ...
;                 for (int m = 0; m < 4; ++m) {
;                     f32x4 c[2];
; #pragma unroll
;                     for (int bj = 0; bj < 2; ++bj) {
;                         const f32x4 h0 = acc[ai][bj][m][eh]; f32x4 p1, p2;
; #pragma unroll
;                         for (int e = 0; e < 4; ++e) {
;                             const float r1 = dpp_ror1(h0[e]), r2 = dpp_ror2(h0[e]);
;                             p1[e] = (fr >= 1) ? r1 : pr1[bj][e]; p2[e] = (fr >= 2) ? r2 : pr2[bj][e];
;                             pr1[bj][e] = r1; pr2[bj][e] = r2;
;                         }
;                         c[bj] = bia[bj] + w[bj][0] * p2 + w[bj][1] * p1 + w[bj][2] * h0;
;                     }
;                     f32x4 o;
; #pragma unroll
;                     for (int e = 0; e < 4; ++e) o[e] = silu_f(c[0][e]) * c[1][e];
;                     pk[m].x = cvt_pk_bf16(o[0], o[1]); pk[m].y = cvt_pk_bf16(o[2], o[3]);
;                 }
; #pragma unroll
;                 for (int m = 0; m < 4; ++m) *(u32x2*)(act + (size_t)(blk0 + 16 * m + fr) * DFF + ch + 4 * eh) = pk[m];
	v_pk_fma_f32 v[102:103], v[102:103], v[148:149], v[112:113]
	v_pk_fma_f32 v[98:99], v[98:99], v[146:147], v[110:111]
	v_add_f32_e32 v112, 1.0, v122
	v_add_f32_e32 v113, 1.0, v123
	v_mul_f32_e32 v122, 0xbfb8aa3b, v104
	v_mul_f32_e32 v123, 0xbfb8aa3b, v105
	v_exp_f32_e32 v122, v122
	v_exp_f32_e32 v123, v123
	v_rcp_f32_e32 v112, v112
	v_rcp_f32_e32 v113, v113
	v_add_f32_e32 v122, 1.0, v122
	v_add_f32_e32 v123, 1.0, v123
	v_rcp_f32_e32 v122, v122
	v_rcp_f32_e32 v123, v123
	v_pk_mul_f32 v[106:107], v[106:107], v[112:113]
	v_mov_b32_dpp v111, v121 row_ror:2 row_mask:0xf bank_mask:0xf bound_ctrl:1
	v_pk_mul_f32 v[98:99], v[106:107], v[98:99]
	v_pk_mul_f32 v[104:105], v[104:105], v[122:123]
	v_cvt_pk_bf16_f32 v226, v98, v99
	v_pk_mul_f32 v[102:103], v[104:105], v[102:103]
	v_mov_b32_dpp v105, v119 row_ror:2 row_mask:0xf bank_mask:0xf bound_ctrl:1
	v_cvt_pk_bf16_f32 v227, v102, v103
	v_mov_b32_dpp v103, v118 row_ror:2 row_mask:0xf bank_mask:0xf bound_ctrl:1
	v_mov_b32_dpp v107, v120 row_ror:2 row_mask:0xf bank_mask:0xf bound_ctrl:1
	v_mov_b32_dpp v102, v118 row_ror:1 row_mask:0xf bank_mask:0xf bound_ctrl:1
	v_cndmask_b32_e64 v104, v127, v103, s[12:13]
	v_mov_b32_dpp v103, v119 row_ror:1 row_mask:0xf bank_mask:0xf bound_ctrl:1
	v_cndmask_b32_e64 v105, v129, v105, s[12:13]
	v_mov_b32_dpp v106, v120 row_ror:1 row_mask:0xf bank_mask:0xf bound_ctrl:1
	v_cndmask_b32_e64 v110, v163, v107, s[12:13]
	v_mov_b32_dpp v107, v121 row_ror:1 row_mask:0xf bank_mask:0xf bound_ctrl:1
	v_cndmask_b32_e64 v111, v165, v111, s[12:13]
	v_cndmask_b32_e64 v102, v102, v126, s[10:11]
	v_cndmask_b32_e64 v103, v103, v128, s[10:11]
	v_cndmask_b32_e64 v106, v106, v162, s[10:11]
	v_cndmask_b32_e64 v107, v107, v164, s[10:11]
	v_pk_fma_f32 v[104:105], v[138:139], v[104:105], v[142:143]
	v_pk_fma_f32 v[110:111], v[140:141], v[110:111], v[144:145]
	v_pk_fma_f32 v[102:103], v[134:135], v[102:103], v[104:105]
	v_pk_fma_f32 v[104:105], v[136:137], v[106:107], v[110:111]
	v_mov_b32_dpp v107, v114 row_ror:2 row_mask:0xf bank_mask:0xf bound_ctrl:1
	v_mov_b32_dpp v111, v115 row_ror:2 row_mask:0xf bank_mask:0xf bound_ctrl:1
	v_pk_fma_f32 v[102:103], v[118:119], v[130:131], v[102:103]
	v_mov_b32_dpp v106, v114 row_ror:1 row_mask:0xf bank_mask:0xf bound_ctrl:1
	v_cndmask_b32_e64 v110, v173, v107, s[12:13]
	v_mov_b32_dpp v107, v115 row_ror:1 row_mask:0xf bank_mask:0xf bound_ctrl:1
	v_cndmask_b32_e64 v111, v174, v111, s[12:13]
	v_mov_b32_dpp v113, v116 row_ror:2 row_mask:0xf bank_mask:0xf bound_ctrl:1
	v_mov_b32_dpp v119, v117 row_ror:2 row_mask:0xf bank_mask:0xf bound_ctrl:1
	v_cndmask_b32_e64 v106, v106, v172, s[10:11]
	v_cndmask_b32_e64 v107, v107, v166, s[10:11]
	v_mov_b32_dpp v112, v116 row_ror:1 row_mask:0xf bank_mask:0xf bound_ctrl:1
	v_cndmask_b32_e64 v118, v175, v113, s[12:13]
	v_mov_b32_dpp v113, v117 row_ror:1 row_mask:0xf bank_mask:0xf bound_ctrl:1
	v_cndmask_b32_e64 v119, v170, v119, s[12:13]
	v_pk_fma_f32 v[110:111], v[154:155], v[110:111], v[158:159]
	v_pk_fma_f32 v[104:105], v[120:121], v[132:133], v[104:105]
	v_cndmask_b32_e64 v112, v112, v167, s[10:11]
	v_cndmask_b32_e64 v113, v113, v168, s[10:11]
	v_pk_fma_f32 v[118:119], v[156:157], v[118:119], v[160:161]
	v_pk_fma_f32 v[106:107], v[150:151], v[106:107], v[110:111]
	v_pk_fma_f32 v[110:111], v[152:153], v[112:113], v[118:119]
	v_mul_f32_e32 v112, 0xbfb8aa3b, v102
	v_mul_f32_e32 v113, 0xbfb8aa3b, v103
	v_pk_fma_f32 v[106:107], v[114:115], v[146:147], v[106:107]
	v_mul_f32_e32 v114, 0xbfb8aa3b, v104
	v_mul_f32_e32 v115, 0xbfb8aa3b, v105
	v_exp_f32_e32 v112, v112
	v_exp_f32_e32 v113, v113
	v_exp_f32_e32 v114, v114
	v_exp_f32_e32 v115, v115
	v_add_f32_e32 v112, 1.0, v112
	v_add_f32_e32 v113, 1.0, v113
	v_add_f32_e32 v114, 1.0, v114
	v_add_f32_e32 v115, 1.0, v115
	v_rcp_f32_e32 v112, v112
	v_rcp_f32_e32 v113, v113
	v_rcp_f32_e32 v114, v114
	v_rcp_f32_e32 v115, v115
	v_pk_fma_f32 v[110:111], v[116:117], v[148:149], v[110:111]
	v_pk_mul_f32 v[102:103], v[102:103], v[112:113]
	v_or_b32_e32 v211, s37, v210
	v_pk_mul_f32 v[104:105], v[104:105], v[114:115]
	v_pk_mul_f32 v[102:103], v[102:103], v[106:107]
	v_pk_mul_f32 v[104:105], v[104:105], v[110:111]
	s_movk_i32 s22, 0x2c00
	v_cvt_pk_bf16_f32 v230, v102, v103
	v_cvt_pk_bf16_f32 v231, v104, v105
	v_mad_i64_i32 v[148:149], s[2:3], v211, s22, v[196:197]
	v_or_b32_e32 v100, 16, v211
	v_mad_i64_i32 v[150:151], s[2:3], v100, s22, v[196:197]
	v_or_b32_e32 v100, 32, v211
	v_mad_i64_i32 v[152:153], s[2:3], v100, s22, v[196:197]
	ds_read_b128 v[106:109], v0 offset:16
	ds_read_b128 v[102:105], v0 offset:1040
	ds_read_b128 v[98:101], v0 offset:2064
	ds_read_b128 v[110:113], v0 offset:3088
	v_or_b32_e32 v116, 48, v211
	v_mad_i64_i32 v[154:155], s[2:3], v116, s22, v[196:197]
	s_and_b64 vcc, exec, s[8:9]
	s_mov_b64 s[2:3], -1
	s_cbranch_vccnz .LBB0_1830
	v_add_co_u32_e32 v114, vcc, 0xb000, v202
	s_mov_b64 s[2:3], 0
	s_nop 0
	v_addc_co_u32_e32 v115, vcc, 0, v203, vcc
	global_load_dwordx4 v[134:137], v[202:203], off offset:16
	global_load_dwordx4 v[130:133], v[114:115], off offset:16

; #define LAS __attribute__((address_space(3)))
;     __device__ __forceinline__ void operator()(const f32x4 (&acc_)[2][2][4][2], const pg8::Unit& u, int wr, int wc, int fr, int fq) const {
;     ...
;             for (int eh = 0; eh < 2; ++eh) {
;                 f32x4 w[2][3], bia[2], hm1[2], hm2[2];
; #pragma unroll
;                 for (int bj = 0; bj < 2; ++bj) {
;                     const int cc = bj * DFF + ch + 4 * eh;
; #pragma unroll
;                     for (int j = 0; j < 3; ++j) w[bj][j] = *(const LAS f32x4*)(cwl + (2 * j + bj) * 128 + 4 * eh);
;                     bia[bj] = *(const LAS f32x4*)(cwl + (6 + bj) * 128 + 4 * eh);
;                     if (!prompt) { const float* ps = past + (size_t)((blk0 - MP) >> 6) * 2 * DFF2 + cc; hm2[bj] = *(const f32x4*)ps; hm1[bj] = *(const f32x4*)(ps + DFF2); }
;                     else if (ai == 0 && wr == 0) { hm1[bj] = (f32x4){0.f, 0.f, 0.f, 0.f}; hm2[bj] = hm1[bj]; }
;                     else { const int pb = ai * 2 + wr - 1; const LAS float* s = hl + (((pb * 4 + wc) * 2 + 0) * 4 + fq) * 16 + bj * 8 + 4 * eh; hm2[bj] = *(const LAS f32x4*)s; hm1[bj] = *(const LAS f32x4*)(s + 64); }
;                 }
;                 u32x2 pk[4]; f32x4 pr1[2], pr2[2];
; #pragma unroll
;                 for (int bj = 0; bj < 2; ++bj)
; #pragma unroll
;                     for (int e = 0; e < 4; ++e) { pr1[bj][e] = hm1[bj][e]; pr2[bj][e] = (fr == 0) ? hm2[bj][e] : hm1[bj][e]; }
; #pragma unroll
;                 for (int m = 0; m < 4; ++m) {
;                     f32x4 c[2];
; #pragma unroll
;                     for (int bj = 0; bj < 2; ++bj) {
;                         const f32x4 h0 = acc[ai][bj][m][eh]; f32x4 p1, p2;
; #pragma unroll
;                         for (int e = 0; e < 4; ++e) {
;                             const float r1 = dpp_ror1(h0[e]), r2 = dpp_ror2(h0[e]);
;                             p1[e] = (fr >= 1) ? r1 : pr1[bj][e]; p2[e] = (fr >= 2) ? r2 : pr2[bj][e];
;                             pr1[bj][e] = r1; pr2[bj][e] = r2;
;                         }
;                         c[bj] = bia[bj] + w[bj][0] * p2 + w[bj][1] * p1 + w[bj][2] * h0;
;                     }
;                     f32x4 o;
; #pragma unroll
;                     for (int e = 0; e < 4; ++e) o[e] = silu_f(c[0][e]) * c[1][e];
;                     pk[m].x = cvt_pk_bf16(o[0], o[1]); pk[m].y = cvt_pk_bf16(o[2], o[3]);
;                 }
.LBB0_1842:
	v_mov_b32_e32 v156, v198
	v_mov_b32_e32 v157, v198
	v_mov_b32_e32 v160, v198
	v_mov_b32_e32 v161, v198
	v_mov_b32_e32 v198, v199
	v_mov_b32_e32 v158, v199
	v_mov_b32_e32 v159, v199
	v_pk_mul_f32 v[70:71], v[70:71], v[156:157]
	v_pk_mul_f32 v[156:157], v[62:63], v[156:157]
	v_pk_mul_f32 v[62:63], v[60:61], v[198:199]
	s_waitcnt vmcnt(0) lgkmcnt(4)
	v_cndmask_b32_e64 v61, v130, v134, s[10:11]
	v_cndmask_b32_e64 v134, v132, v136, s[10:11]
	s_waitcnt lgkmcnt(0)
	v_cndmask_b32_e64 v136, v138, v142, s[10:11]
	v_cndmask_b32_e64 v142, v140, v144, s[10:11]
	v_mov_b32_dpp v144, v94 row_ror:1 row_mask:0xf bank_mask:0xf bound_ctrl:1
	v_mov_b32_dpp v162, v96 row_ror:1 row_mask:0xf bank_mask:0xf bound_ctrl:1
	v_mov_b32_dpp v163, v96 row_ror:2 row_mask:0xf bank_mask:0xf bound_ctrl:1
	v_pk_mul_f32 v[72:73], v[72:73], v[160:161]
	v_pk_mul_f32 v[160:161], v[64:65], v[160:161]
	v_pk_mul_f32 v[64:65], v[68:69], v[198:199]
	v_pk_mul_f32 v[66:67], v[66:67], v[158:159]
	v_pk_mul_f32 v[58:59], v[58:59], v[158:159]
	v_cndmask_b32_e64 v69, v131, v135, s[10:11]
	v_cndmask_b32_e64 v135, v133, v137, s[10:11]
	v_cndmask_b32_e64 v137, v139, v143, s[10:11]
	v_cndmask_b32_e64 v143, v141, v145, s[10:11]
	v_mov_b32_dpp v145, v94 row_ror:2 row_mask:0xf bank_mask:0xf bound_ctrl:1
	v_cndmask_b32_e64 v60, v144, v130, s[10:11]
	v_mov_b32_dpp v158, v95 row_ror:1 row_mask:0xf bank_mask:0xf bound_ctrl:1
	v_mov_b32_dpp v159, v95 row_ror:2 row_mask:0xf bank_mask:0xf bound_ctrl:1
	v_cndmask_b32_e64 v130, v162, v132, s[10:11]
	v_cndmask_b32_e64 v132, v134, v163, s[12:13]
	v_mov_b32_dpp v134, v97 row_ror:1 row_mask:0xf bank_mask:0xf bound_ctrl:1
	v_mov_b32_dpp v164, v97 row_ror:2 row_mask:0xf bank_mask:0xf bound_ctrl:1
	v_cndmask_b32_e64 v68, v61, v145, s[12:13]
	v_cndmask_b32_e64 v61, v158, v131, s[10:11]
	v_cndmask_b32_e64 v69, v69, v159, s[12:13]
	v_cndmask_b32_e64 v131, v134, v133, s[10:11]
	v_cndmask_b32_e64 v133, v135, v164, s[12:13]
	v_pk_fma_f32 v[132:133], v[108:109], v[132:133], v[112:113]
	v_pk_fma_f32 v[68:69], v[106:107], v[68:69], v[110:111]
	v_mov_b32_dpp v165, v90 row_ror:2 row_mask:0xf bank_mask:0xf bound_ctrl:1
	v_pk_fma_f32 v[60:61], v[102:103], v[60:61], v[68:69]
	v_pk_fma_f32 v[68:69], v[104:105], v[130:131], v[132:133]
	v_mov_b32_dpp v135, v90 row_ror:1 row_mask:0xf bank_mask:0xf bound_ctrl:1
	v_pk_fma_f32 v[68:69], v[96:97], v[100:101], v[68:69]
	v_cndmask_b32_e64 v96, v136, v165, s[12:13]
	v_mov_b32_dpp v136, v91 row_ror:1 row_mask:0xf bank_mask:0xf bound_ctrl:1
	v_pk_fma_f32 v[60:61], v[94:95], v[98:99], v[60:61]
	v_cndmask_b32_e64 v94, v135, v138, s[10:11]
	v_mov_b32_dpp v138, v91 row_ror:2 row_mask:0xf bank_mask:0xf bound_ctrl:1
	v_cndmask_b32_e64 v95, v136, v139, s[10:11]
	v_mov_b32_dpp v139, v92 row_ror:2 row_mask:0xf bank_mask:0xf bound_ctrl:1
	v_cndmask_b32_e64 v97, v137, v138, s[12:13]
	v_mov_b32_dpp v137, v92 row_ror:1 row_mask:0xf bank_mask:0xf bound_ctrl:1
	v_cndmask_b32_e64 v132, v142, v139, s[12:13]
	v_mov_b32_dpp v142, v93 row_ror:2 row_mask:0xf bank_mask:0xf bound_ctrl:1
	v_cndmask_b32_e64 v130, v137, v140, s[10:11]
	v_mov_b32_dpp v140, v93 row_ror:1 row_mask:0xf bank_mask:0xf bound_ctrl:1
	v_cndmask_b32_e64 v133, v143, v142, s[12:13]
	v_cndmask_b32_e64 v131, v140, v141, s[10:11]
	v_pk_fma_f32 v[132:133], v[124:125], v[132:133], v[128:129]
	v_pk_fma_f32 v[96:97], v[122:123], v[96:97], v[126:127]
	v_mov_b32_dpp v143, v73 row_ror:2 row_mask:0xf bank_mask:0xf bound_ctrl:1
	v_pk_fma_f32 v[94:95], v[118:119], v[94:95], v[96:97]
	v_pk_fma_f32 v[96:97], v[120:121], v[130:131], v[132:133]
	v_mul_f32_e32 v130, 0xbfb8aa3b, v60
	v_mul_f32_e32 v131, 0xbfb8aa3b, v61
	v_exp_f32_e32 v130, v130
	v_exp_f32_e32 v131, v131
	v_pk_fma_f32 v[92:93], v[92:93], v[116:117], v[96:97]
	v_pk_fma_f32 v[90:91], v[90:91], v[114:115], v[94:95]
	v_add_f32_e32 v96, 1.0, v130
	v_add_f32_e32 v97, 1.0, v131
	v_mul_f32_e32 v130, 0xbfb8aa3b, v68
	v_mul_f32_e32 v131, 0xbfb8aa3b, v69
	v_exp_f32_e32 v130, v130
	v_exp_f32_e32 v131, v131
	v_rcp_f32_e32 v96, v96
	v_rcp_f32_e32 v97, v97
	v_add_f32_e32 v130, 1.0, v130
	v_add_f32_e32 v131, 1.0, v131
	v_rcp_f32_e32 v130, v130
	v_rcp_f32_e32 v131, v131
	v_pk_mul_f32 v[60:61], v[60:61], v[96:97]
	v_mov_b32_dpp v97, v70 row_ror:2 row_mask:0xf bank_mask:0xf bound_ctrl:1
	v_mov_b32_dpp v133, v72 row_ror:2 row_mask:0xf bank_mask:0xf bound_ctrl:1
	v_pk_mul_f32 v[68:69], v[68:69], v[130:131]
	v_mov_b32_dpp v131, v71 row_ror:2 row_mask:0xf bank_mask:0xf bound_ctrl:1
	v_pk_mul_f32 v[60:61], v[60:61], v[90:91]
	v_pk_mul_f32 v[68:69], v[68:69], v[92:93]
	v_mov_b32_dpp v96, v70 row_ror:1 row_mask:0xf bank_mask:0xf bound_ctrl:1
	v_cndmask_b32_e64 v90, v145, v97, s[12:13]
	v_mov_b32_dpp v130, v71 row_ror:1 row_mask:0xf bank_mask:0xf bound_ctrl:1
	v_cndmask_b32_e64 v91, v159, v131, s[12:13]
	v_mov_b32_dpp v132, v72 row_ror:1 row_mask:0xf bank_mask:0xf bound_ctrl:1
	v_cndmask_b32_e64 v94, v163, v133, s[12:13]
	v_mov_b32_dpp v141, v73 row_ror:1 row_mask:0xf bank_mask:0xf bound_ctrl:1
	v_cndmask_b32_e64 v95, v164, v143, s[12:13]
	v_cvt_pk_bf16_f32 v220, v60, v61
	v_cvt_pk_bf16_f32 v221, v68, v69
	v_cndmask_b32_e64 v68, v96, v144, s[10:11]
	v_cndmask_b32_e64 v69, v130, v158, s[10:11]
	v_cndmask_b32_e64 v92, v132, v162, s[10:11]
	v_cndmask_b32_e64 v93, v141, v134, s[10:11]
	v_pk_fma_f32 v[94:95], v[108:109], v[94:95], v[112:113]
	v_pk_fma_f32 v[90:91], v[106:107], v[90:91], v[110:111]
	v_mov_b32_dpp v134, v156 row_ror:1 row_mask:0xf bank_mask:0xf bound_ctrl:1
	v_pk_fma_f32 v[68:69], v[102:103], v[68:69], v[90:91]
	v_pk_fma_f32 v[90:91], v[104:105], v[92:93], v[94:95]
	v_mov_b32_dpp v145, v157 row_ror:2 row_mask:0xf bank_mask:0xf bound_ctrl:1
; __device__ __forceinline__ unsigned cvt_pk_bf16(float lo, float hi) { const f32x2 v = {lo, hi}; unsigned r = __builtin_bit_cast(unsigned, __builtin_convertvector(v, bf16x2_t)); asm volatile("" : "+v"(r)); return r; }
; __device__ __forceinline__ float silu_f(float x) { return x * __builtin_amdgcn_rcpf(1.0f + __expf(-x)); }
; __device__ __forceinline__ float dpp_ror1(float x) { return __builtin_bit_cast(float, __builtin_amdgcn_update_dpp(0, __builtin_bit_cast(int, x), 0x121, 0xf, 0xf, true)); }
; __device__ __forceinline__ float dpp_ror2(float x) { return __builtin_bit_cast(float, __builtin_amdgcn_update_dpp(0, __builtin_bit_cast(int, x), 0x122, 0xf, 0xf, true)); }
;     __device__ __forceinline__ void operator()(const f32x4 (&acc_)[2][2][4][2], const pg8::Unit& u, int wr, int wc, int fr, int fq) const {
;     ...
;                 for (int m = 0; m < 4; ++m) {
;                     f32x4 c[2];
; #pragma unroll
;                     for (int bj = 0; bj < 2; ++bj) {
;                         const f32x4 h0 = acc[ai][bj][m][eh]; f32x4 p1, p2;
; #pragma unroll
;                         for (int e = 0; e < 4; ++e) {
;                             const float r1 = dpp_ror1(h0[e]), r2 = dpp_ror2(h0[e]);
;                             p1[e] = (fr >= 1) ? r1 : pr1[bj][e]; p2[e] = (fr >= 2) ? r2 : pr2[bj][e];
;                             pr1[bj][e] = r1; pr2[bj][e] = r2;
;                         }
;                         c[bj] = bia[bj] + w[bj][0] * p2 + w[bj][1] * p1 + w[bj][2] * h0;
;                     }
;                     f32x4 o;
; #pragma unroll
;                     for (int e = 0; e < 4; ++e) o[e] = silu_f(c[0][e]) * c[1][e];
;                     pk[m].x = cvt_pk_bf16(o[0], o[1]); pk[m].y = cvt_pk_bf16(o[2], o[3]);
;                 }
	v_pk_fma_f32 v[72:73], v[72:73], v[100:101], v[90:91]
	v_pk_fma_f32 v[68:69], v[70:71], v[98:99], v[68:69]
	v_cndmask_b32_e64 v70, v134, v135, s[10:11]
	v_mov_b32_dpp v135, v157 row_ror:1 row_mask:0xf bank_mask:0xf bound_ctrl:1
	v_cndmask_b32_e64 v91, v138, v145, s[12:13]
	v_mov_b32_dpp v138, v160 row_ror:2 row_mask:0xf bank_mask:0xf bound_ctrl:1
	v_mov_b32_dpp v144, v156 row_ror:2 row_mask:0xf bank_mask:0xf bound_ctrl:1
	v_cndmask_b32_e64 v71, v135, v136, s[10:11]
	v_mov_b32_dpp v136, v160 row_ror:1 row_mask:0xf bank_mask:0xf bound_ctrl:1
	v_cndmask_b32_e64 v94, v139, v138, s[12:13]
	v_mov_b32_dpp v139, v161 row_ror:2 row_mask:0xf bank_mask:0xf bound_ctrl:1
	v_cndmask_b32_e64 v90, v165, v144, s[12:13]
	v_cndmask_b32_e64 v92, v136, v137, s[10:11]
	v_mov_b32_dpp v137, v161 row_ror:1 row_mask:0xf bank_mask:0xf bound_ctrl:1
	v_cndmask_b32_e64 v95, v142, v139, s[12:13]
	v_cndmask_b32_e64 v93, v137, v140, s[10:11]
	v_pk_fma_f32 v[94:95], v[124:125], v[94:95], v[128:129]
	v_pk_fma_f32 v[90:91], v[122:123], v[90:91], v[126:127]
	v_mov_b32_dpp v140, v58 row_ror:1 row_mask:0xf bank_mask:0xf bound_ctrl:1
	v_pk_fma_f32 v[70:71], v[118:119], v[70:71], v[90:91]
	v_pk_fma_f32 v[90:91], v[120:121], v[92:93], v[94:95]
	v_mul_f32_e32 v92, 0xbfb8aa3b, v68
	v_mul_f32_e32 v93, 0xbfb8aa3b, v69
	v_exp_f32_e32 v92, v92
	v_exp_f32_e32 v93, v93
	v_mul_f32_e32 v94, 0xbfb8aa3b, v72
	v_mul_f32_e32 v95, 0xbfb8aa3b, v73
	v_exp_f32_e32 v94, v94
	v_exp_f32_e32 v95, v95
	v_add_f32_e32 v92, 1.0, v92
	v_add_f32_e32 v93, 1.0, v93
	v_rcp_f32_e32 v92, v92
	v_rcp_f32_e32 v93, v93
	v_add_f32_e32 v94, 1.0, v94
	v_add_f32_e32 v95, 1.0, v95
	v_rcp_f32_e32 v94, v94
	v_rcp_f32_e32 v95, v95
	v_pk_fma_f32 v[70:71], v[156:157], v[114:115], v[70:71]
	v_pk_mul_f32 v[68:69], v[68:69], v[92:93]
	v_pk_fma_f32 v[90:91], v[160:161], v[116:117], v[90:91]
	v_pk_mul_f32 v[68:69], v[68:69], v[70:71]
	v_pk_mul_f32 v[70:71], v[72:73], v[94:95]
	v_mov_b32_dpp v95, v66 row_ror:2 row_mask:0xf bank_mask:0xf bound_ctrl:1
	v_pk_mul_f32 v[70:71], v[70:71], v[90:91]
	v_mov_b32_dpp v94, v66 row_ror:1 row_mask:0xf bank_mask:0xf bound_ctrl:1
	v_cndmask_b32_e64 v72, v97, v95, s[12:13]
	v_mov_b32_dpp v97, v67 row_ror:2 row_mask:0xf bank_mask:0xf bound_ctrl:1
	v_cvt_pk_bf16_f32 v224, v68, v69
	v_cvt_pk_bf16_f32 v225, v70, v71
	v_cndmask_b32_e64 v70, v94, v96, s[10:11]
	v_mov_b32_dpp v96, v67 row_ror:1 row_mask:0xf bank_mask:0xf bound_ctrl:1
	v_cndmask_b32_e64 v73, v131, v97, s[12:13]
	v_mov_b32_dpp v131, v64 row_ror:2 row_mask:0xf bank_mask:0xf bound_ctrl:1
	v_cndmask_b32_e64 v71, v96, v130, s[10:11]
	v_mov_b32_dpp v130, v64 row_ror:1 row_mask:0xf bank_mask:0xf bound_ctrl:1
	v_cndmask_b32_e64 v92, v133, v131, s[12:13]
	v_mov_b32_dpp v133, v65 row_ror:2 row_mask:0xf bank_mask:0xf bound_ctrl:1
	v_pk_fma_f32 v[72:73], v[106:107], v[72:73], v[110:111]
	v_cndmask_b32_e64 v90, v130, v132, s[10:11]
	v_mov_b32_dpp v132, v65 row_ror:1 row_mask:0xf bank_mask:0xf bound_ctrl:1
	v_cndmask_b32_e64 v93, v143, v133, s[12:13]
	v_pk_fma_f32 v[70:71], v[102:103], v[70:71], v[72:73]
	v_cndmask_b32_e64 v91, v132, v141, s[10:11]
	v_pk_fma_f32 v[92:93], v[108:109], v[92:93], v[112:113]
	v_pk_fma_f32 v[66:67], v[66:67], v[98:99], v[70:71]
	v_cndmask_b32_e64 v70, v140, v134, s[10:11]
	v_mov_b32_dpp v134, v59 row_ror:1 row_mask:0xf bank_mask:0xf bound_ctrl:1
	v_mov_b32_dpp v143, v62 row_ror:2 row_mask:0xf bank_mask:0xf bound_ctrl:1
	v_pk_fma_f32 v[90:91], v[104:105], v[90:91], v[92:93]
	v_cndmask_b32_e64 v71, v134, v135, s[10:11]
	v_mov_b32_dpp v135, v62 row_ror:1 row_mask:0xf bank_mask:0xf bound_ctrl:1
	v_cndmask_b32_e64 v92, v138, v143, s[12:13]
	v_mov_b32_dpp v138, v63 row_ror:2 row_mask:0xf bank_mask:0xf bound_ctrl:1
	v_pk_fma_f32 v[64:65], v[64:65], v[100:101], v[90:91]
	v_mov_b32_dpp v141, v58 row_ror:2 row_mask:0xf bank_mask:0xf bound_ctrl:1
	v_mov_b32_dpp v142, v59 row_ror:2 row_mask:0xf bank_mask:0xf bound_ctrl:1
	v_cndmask_b32_e64 v90, v135, v136, s[10:11]
	v_mov_b32_dpp v136, v63 row_ror:1 row_mask:0xf bank_mask:0xf bound_ctrl:1
	v_cndmask_b32_e64 v93, v139, v138, s[12:13]
	v_cndmask_b32_e64 v72, v144, v141, s[12:13]
	v_cndmask_b32_e64 v73, v145, v142, s[12:13]
	v_cndmask_b32_e64 v91, v136, v137, s[10:11]
	v_pk_fma_f32 v[92:93], v[124:125], v[92:93], v[128:129]
	v_pk_fma_f32 v[72:73], v[122:123], v[72:73], v[126:127]
	v_pk_fma_f32 v[90:91], v[120:121], v[90:91], v[92:93]
	v_pk_fma_f32 v[70:71], v[118:119], v[70:71], v[72:73]
	v_mul_f32_e32 v72, 0xbfb8aa3b, v66
	v_mul_f32_e32 v73, 0xbfb8aa3b, v67
	v_pk_fma_f32 v[62:63], v[62:63], v[116:117], v[90:91]
	v_mul_f32_e32 v90, 0xbfb8aa3b, v64
	v_mul_f32_e32 v91, 0xbfb8aa3b, v65
	v_exp_f32_e32 v72, v72
; #define LAS __attribute__((address_space(3)))
; __device__ __forceinline__ unsigned cvt_pk_bf16(float lo, float hi) { const f32x2 v = {lo, hi}; unsigned r = __builtin_bit_cast(unsigned, __builtin_convertvector(v, bf16x2_t)); asm volatile("" : "+v"(r)); return r; }
; __device__ __forceinline__ float silu_f(float x) { return x * __builtin_amdgcn_rcpf(1.0f + __expf(-x)); }
;     __device__ __forceinline__ void operator()(const f32x4 (&acc_)[2][2][4][2], const pg8::Unit& u, int wr, int wc, int fr, int fq) const {
;     ...
;                     const int cc = bj * DFF + ch + 4 * eh;
; #pragma unroll
;                     for (int j = 0; j < 3; ++j) w[bj][j] = *(const LAS f32x4*)(cwl + (2 * j + bj) * 128 + 4 * eh);
;                     bia[bj] = *(const LAS f32x4*)(cwl + (6 + bj) * 128 + 4 * eh);
;                     if (!prompt) { const float* ps = past + (size_t)((blk0 - MP) >> 6) * 2 * DFF2 + cc; hm2[bj] = *(const f32x4*)ps; hm1[bj] = *(const f32x4*)(ps + DFF2); }
;                     else if (ai == 0 && wr == 0) { hm1[bj] = (f32x4){0.f, 0.f, 0.f, 0.f}; hm2[bj] = hm1[bj]; }
;                     else { const int pb = ai * 2 + wr - 1; const LAS float* s = hl + (((pb * 4 + wc) * 2 + 0) * 4 + fq) * 16 + bj * 8 + 4 * eh; hm2[bj] = *(const LAS f32x4*)s; hm1[bj] = *(const LAS f32x4*)(s + 64); }
;     ...
;                 for (int m = 0; m < 4; ++m) {
;                     f32x4 c[2];
; #pragma unroll
;                     for (int bj = 0; bj < 2; ++bj) {
;                         const f32x4 h0 = acc[ai][bj][m][eh]; f32x4 p1, p2;
; #pragma unroll
;                         for (int e = 0; e < 4; ++e) {
;                             const float r1 = dpp_ror1(h0[e]), r2 = dpp_ror2(h0[e]);
;                             p1[e] = (fr >= 1) ? r1 : pr1[bj][e]; p2[e] = (fr >= 2) ? r2 : pr2[bj][e];
;                             pr1[bj][e] = r1; pr2[bj][e] = r2;
;                         }
;                         c[bj] = bia[bj] + w[bj][0] * p2 + w[bj][1] * p1 + w[bj][2] * h0;
;                     }
;                     f32x4 o;
; #pragma unroll
;                     for (int e = 0; e < 4; ++e) o[e] = silu_f(c[0][e]) * c[1][e];
;                     pk[m].x = cvt_pk_bf16(o[0], o[1]); pk[m].y = cvt_pk_bf16(o[2], o[3]);
;                 }
; #pragma unroll
;                 for (int m = 0; m < 4; ++m) *(u32x2*)(act + (size_t)(blk0 + 16 * m + fr) * DFF + ch + 4 * eh) = pk[m];
	v_exp_f32_e32 v73, v73
	v_exp_f32_e32 v90, v90
	v_exp_f32_e32 v91, v91
	v_add_f32_e32 v72, 1.0, v72
	v_add_f32_e32 v73, 1.0, v73
	v_add_f32_e32 v90, 1.0, v90
	v_add_f32_e32 v91, 1.0, v91
	v_rcp_f32_e32 v72, v72
	v_rcp_f32_e32 v73, v73
	v_rcp_f32_e32 v90, v90
	v_rcp_f32_e32 v91, v91
	v_pk_fma_f32 v[58:59], v[58:59], v[114:115], v[70:71]
	v_pk_mul_f32 v[66:67], v[66:67], v[72:73]
	v_mov_b32_dpp v71, v89 row_ror:2 row_mask:0xf bank_mask:0xf bound_ctrl:1
	v_pk_mul_f32 v[64:65], v[64:65], v[90:91]
	v_pk_mul_f32 v[58:59], v[66:67], v[58:59]
	v_pk_mul_f32 v[62:63], v[64:65], v[62:63]
	v_cvt_pk_bf16_f32 v228, v58, v59
	v_cvt_pk_bf16_f32 v229, v62, v63
	v_mov_b32_dpp v63, v86 row_ror:2 row_mask:0xf bank_mask:0xf bound_ctrl:1
	v_mov_b32_dpp v65, v87 row_ror:2 row_mask:0xf bank_mask:0xf bound_ctrl:1
	v_mov_b32_dpp v62, v86 row_ror:1 row_mask:0xf bank_mask:0xf bound_ctrl:1
	v_cndmask_b32_e64 v64, v95, v63, s[12:13]
	v_mov_b32_dpp v63, v87 row_ror:1 row_mask:0xf bank_mask:0xf bound_ctrl:1
	v_cndmask_b32_e64 v65, v97, v65, s[12:13]
	v_mov_b32_dpp v67, v88 row_ror:2 row_mask:0xf bank_mask:0xf bound_ctrl:1
	v_cndmask_b32_e64 v62, v62, v94, s[10:11]
	v_cndmask_b32_e64 v63, v63, v96, s[10:11]
	v_mov_b32_dpp v66, v88 row_ror:1 row_mask:0xf bank_mask:0xf bound_ctrl:1
	v_cndmask_b32_e64 v70, v131, v67, s[12:13]
	v_mov_b32_dpp v67, v89 row_ror:1 row_mask:0xf bank_mask:0xf bound_ctrl:1
	v_cndmask_b32_e64 v71, v133, v71, s[12:13]
	v_pk_fma_f32 v[64:65], v[106:107], v[64:65], v[110:111]
	v_cndmask_b32_e64 v66, v66, v130, s[10:11]
	v_cndmask_b32_e64 v67, v67, v132, s[10:11]
	v_pk_fma_f32 v[70:71], v[108:109], v[70:71], v[112:113]
	v_pk_fma_f32 v[62:63], v[102:103], v[62:63], v[64:65]
	v_pk_fma_f32 v[64:65], v[104:105], v[66:67], v[70:71]
	v_pk_fma_f32 v[62:63], v[86:87], v[98:99], v[62:63]
	v_mov_b32_dpp v67, v82 row_ror:2 row_mask:0xf bank_mask:0xf bound_ctrl:1
	v_mov_b32_dpp v71, v83 row_ror:2 row_mask:0xf bank_mask:0xf bound_ctrl:1
	v_mov_b32_dpp v73, v84 row_ror:2 row_mask:0xf bank_mask:0xf bound_ctrl:1
	v_mov_b32_dpp v87, v85 row_ror:2 row_mask:0xf bank_mask:0xf bound_ctrl:1
	v_mov_b32_dpp v66, v82 row_ror:1 row_mask:0xf bank_mask:0xf bound_ctrl:1
	v_cndmask_b32_e64 v70, v141, v67, s[12:13]
	v_mov_b32_dpp v67, v83 row_ror:1 row_mask:0xf bank_mask:0xf bound_ctrl:1
	v_cndmask_b32_e64 v71, v142, v71, s[12:13]
	v_mov_b32_dpp v72, v84 row_ror:1 row_mask:0xf bank_mask:0xf bound_ctrl:1
	v_cndmask_b32_e64 v86, v143, v73, s[12:13]
	v_mov_b32_dpp v73, v85 row_ror:1 row_mask:0xf bank_mask:0xf bound_ctrl:1
	v_cndmask_b32_e64 v87, v138, v87, s[12:13]
	v_cndmask_b32_e64 v66, v66, v140, s[10:11]
	v_cndmask_b32_e64 v67, v67, v134, s[10:11]
	v_cndmask_b32_e64 v72, v72, v135, s[10:11]
	v_cndmask_b32_e64 v73, v73, v136, s[10:11]
	v_pk_fma_f32 v[86:87], v[124:125], v[86:87], v[128:129]
	v_pk_fma_f32 v[70:71], v[122:123], v[70:71], v[126:127]
	v_pk_fma_f32 v[64:65], v[88:89], v[100:101], v[64:65]
	v_pk_fma_f32 v[66:67], v[118:119], v[66:67], v[70:71]
	v_pk_fma_f32 v[70:71], v[120:121], v[72:73], v[86:87]
	v_mul_f32_e32 v72, 0xbfb8aa3b, v62
	v_mul_f32_e32 v73, 0xbfb8aa3b, v63
	v_pk_fma_f32 v[70:71], v[84:85], v[116:117], v[70:71]
	v_mul_f32_e32 v84, 0xbfb8aa3b, v64
	v_mul_f32_e32 v85, 0xbfb8aa3b, v65
	v_exp_f32_e32 v72, v72
	v_exp_f32_e32 v73, v73
	v_exp_f32_e32 v84, v84
	v_exp_f32_e32 v85, v85
	v_add_f32_e32 v72, 1.0, v72
	v_add_f32_e32 v73, 1.0, v73
	v_add_f32_e32 v84, 1.0, v84
	v_add_f32_e32 v85, 1.0, v85
	v_rcp_f32_e32 v72, v72
	v_rcp_f32_e32 v73, v73
	v_rcp_f32_e32 v84, v84
	v_rcp_f32_e32 v85, v85
	v_pk_fma_f32 v[66:67], v[82:83], v[114:115], v[66:67]
	v_pk_mul_f32 v[62:63], v[62:63], v[72:73]
	v_pk_mul_f32 v[64:65], v[64:65], v[84:85]
	v_pk_mul_f32 v[62:63], v[62:63], v[66:67]
	v_pk_mul_f32 v[64:65], v[64:65], v[70:71]
	v_cvt_pk_bf16_f32 v232, v62, v63
	v_cvt_pk_bf16_f32 v233, v64, v65
	global_store_dwordx4 v[148:149], v[218:221], off
	global_store_dwordx4 v[150:151], v[222:225], off
	global_store_dwordx4 v[152:153], v[226:229], off
	global_store_dwordx4 v[154:155], v[230:233], off
	ds_read_b128 v[70:73], v0
	ds_read_b128 v[66:69], v0 offset:1024
	ds_read_b128 v[62:65], v0 offset:2048
	ds_read_b128 v[82:85], v0 offset:3072
	s_add_i32 s2, s37, 0xffffc080
	s_ashr_i32 s2, s2, 6
	s_mul_hi_i32 s3, s2, 0x16000
	s_mul_i32 s2, s2, 0x16000
	s_add_u32 s14, s81, s2
	s_addc_u32 s15, s92, s3
	s_mov_b64 s[2:3], -1
	s_and_b64 vcc, exec, s[8:9]
	v_lshl_add_u64 v[114:115], v[194:195], 2, s[14:15]
	s_cbranch_vccnz .LBB0_1844
	v_add_co_u32_e32 v58, vcc, 0xb000, v114
	s_mov_b64 s[2:3], 0
	s_nop 0
	v_addc_co_u32_e32 v59, vcc, 0, v115, vcc
	global_load_dwordx4 v[106:109], v[114:115], off
	global_load_dwordx4 v[98:101], v[58:59], off

; #define LAS __attribute__((address_space(3)))
;     __device__ __forceinline__ void operator()(const f32x4 (&acc_)[2][2][4][2], const pg8::Unit& u, int wr, int wc, int fr, int fq) const {
;     ...
;             for (int eh = 0; eh < 2; ++eh) {
;                 f32x4 w[2][3], bia[2], hm1[2], hm2[2];
; #pragma unroll
;                 for (int bj = 0; bj < 2; ++bj) {
;                     const int cc = bj * DFF + ch + 4 * eh;
; #pragma unroll
;                     for (int j = 0; j < 3; ++j) w[bj][j] = *(const LAS f32x4*)(cwl + (2 * j + bj) * 128 + 4 * eh);
;                     bia[bj] = *(const LAS f32x4*)(cwl + (6 + bj) * 128 + 4 * eh);
;                     if (!prompt) { const float* ps = past + (size_t)((blk0 - MP) >> 6) * 2 * DFF2 + cc; hm2[bj] = *(const f32x4*)ps; hm1[bj] = *(const f32x4*)(ps + DFF2); }
;                     else if (ai == 0 && wr == 0) { hm1[bj] = (f32x4){0.f, 0.f, 0.f, 0.f}; hm2[bj] = hm1[bj]; }
;                     else { const int pb = ai * 2 + wr - 1; const LAS float* s = hl + (((pb * 4 + wc) * 2 + 0) * 4 + fq) * 16 + bj * 8 + 4 * eh; hm2[bj] = *(const LAS f32x4*)s; hm1[bj] = *(const LAS f32x4*)(s + 64); }
;                 }
;                 u32x2 pk[4]; f32x4 pr1[2], pr2[2];
; #pragma unroll
;                 for (int bj = 0; bj < 2; ++bj)
; #pragma unroll
;                     for (int e = 0; e < 4; ++e) { pr1[bj][e] = hm1[bj][e]; pr2[bj][e] = (fr == 0) ? hm2[bj][e] : hm1[bj][e]; }
; #pragma unroll
;                 for (int m = 0; m < 4; ++m) {
;                     f32x4 c[2];
; #pragma unroll
;                     for (int bj = 0; bj < 2; ++bj) {
;                         const f32x4 h0 = acc[ai][bj][m][eh]; f32x4 p1, p2;
; #pragma unroll
;                         for (int e = 0; e < 4; ++e) {
;                             const float r1 = dpp_ror1(h0[e]), r2 = dpp_ror2(h0[e]);
;                             p1[e] = (fr >= 1) ? r1 : pr1[bj][e]; p2[e] = (fr >= 2) ? r2 : pr2[bj][e];
;                             pr1[bj][e] = r1; pr2[bj][e] = r2;
;                         }
;                         c[bj] = bia[bj] + w[bj][0] * p2 + w[bj][1] * p1 + w[bj][2] * h0;
;                     }
;                     f32x4 o;
; #pragma unroll
;                     for (int e = 0; e < 4; ++e) o[e] = silu_f(c[0][e]) * c[1][e];
;                     pk[m].x = cvt_pk_bf16(o[0], o[1]); pk[m].y = cvt_pk_bf16(o[2], o[3]);
;                 }
.LBB0_1850:
	v_pk_mul_f32 v[46:47], v[46:47], v[192:193] op_sel_hi:[1,0]
	v_pk_mul_f32 v[116:117], v[34:35], v[192:193] op_sel_hi:[1,0]
	v_mov_b32_e32 v34, v193
	v_pk_mul_f32 v[48:49], v[48:49], v[192:193] op_sel_hi:[1,0]
	v_pk_mul_f32 v[44:45], v[44:45], v[34:35] op_sel_hi:[1,0]
	v_pk_mul_f32 v[42:43], v[42:43], v[34:35] op_sel_hi:[1,0]
	v_pk_mul_f32 v[118:119], v[32:33], v[34:35] op_sel_hi:[1,0]
	v_pk_mul_f32 v[120:121], v[30:31], v[34:35] op_sel_hi:[1,0]
	v_pk_mul_f32 v[34:35], v[38:39], v[190:191] op_sel_hi:[1,0]
	v_pk_mul_f32 v[30:31], v[28:29], v[190:191] op_sel_hi:[1,0]
	v_pk_mul_f32 v[28:29], v[26:27], v[190:191] op_sel_hi:[1,0]
	s_waitcnt vmcnt(0) lgkmcnt(4)
	v_cndmask_b32_e64 v27, v98, v106, s[10:11]
	v_cndmask_b32_e64 v39, v99, v107, s[10:11]
	v_cndmask_b32_e64 v106, v101, v109, s[10:11]
	s_waitcnt lgkmcnt(0)
	v_cndmask_b32_e64 v109, v104, v112, s[10:11]
	v_mov_b32_dpp v112, v46 row_ror:2 row_mask:0xf bank_mask:0xf bound_ctrl:1
	v_mov_b32_dpp v123, v47 row_ror:2 row_mask:0xf bank_mask:0xf bound_ctrl:1
	v_pk_mul_f32 v[32:33], v[40:41], v[190:191] op_sel_hi:[1,0]
	v_cndmask_b32_e64 v41, v100, v108, s[10:11]
	v_cndmask_b32_e64 v107, v102, v110, s[10:11]
	v_cndmask_b32_e64 v108, v103, v111, s[10:11]
	v_cndmask_b32_e64 v110, v105, v113, s[10:11]
	v_mov_b32_dpp v111, v46 row_ror:1 row_mask:0xf bank_mask:0xf bound_ctrl:1
	v_cndmask_b32_e64 v38, v27, v112, s[12:13]
	v_mov_b32_dpp v113, v47 row_ror:1 row_mask:0xf bank_mask:0xf bound_ctrl:1
	v_cndmask_b32_e64 v39, v39, v123, s[12:13]
	v_mov_b32_dpp v124, v48 row_ror:1 row_mask:0xf bank_mask:0xf bound_ctrl:1
	v_mov_b32_dpp v125, v48 row_ror:2 row_mask:0xf bank_mask:0xf bound_ctrl:1
	v_mov_b32_dpp v126, v49 row_ror:2 row_mask:0xf bank_mask:0xf bound_ctrl:1
	v_cndmask_b32_e64 v26, v111, v98, s[10:11]
	v_cndmask_b32_e64 v27, v113, v99, s[10:11]
	v_cndmask_b32_e64 v40, v124, v100, s[10:11]
	v_cndmask_b32_e64 v98, v41, v125, s[12:13]
	v_mov_b32_dpp v100, v49 row_ror:1 row_mask:0xf bank_mask:0xf bound_ctrl:1
	v_cndmask_b32_e64 v99, v106, v126, s[12:13]
	v_pk_fma_f32 v[38:39], v[70:71], v[38:39], v[82:83]
	v_cndmask_b32_e64 v41, v100, v101, s[10:11]
	v_pk_fma_f32 v[98:99], v[72:73], v[98:99], v[84:85]
	v_pk_fma_f32 v[26:27], v[66:67], v[26:27], v[38:39]
	v_mov_b32_dpp v106, v116 row_ror:2 row_mask:0xf bank_mask:0xf bound_ctrl:1
	v_pk_mul_f32 v[36:37], v[36:37], v[192:193] op_sel_hi:[1,0]
	v_pk_fma_f32 v[40:41], v[68:69], v[40:41], v[98:99]
	v_pk_fma_f32 v[26:27], v[46:47], v[62:63], v[26:27]
	v_mov_b32_dpp v101, v116 row_ror:1 row_mask:0xf bank_mask:0xf bound_ctrl:1
	v_cndmask_b32_e64 v46, v107, v106, s[12:13]
	v_mov_b32_dpp v107, v117 row_ror:2 row_mask:0xf bank_mask:0xf bound_ctrl:1
	v_pk_fma_f32 v[38:39], v[48:49], v[64:65], v[40:41]
	v_cndmask_b32_e64 v40, v101, v102, s[10:11]
	v_mov_b32_dpp v102, v117 row_ror:1 row_mask:0xf bank_mask:0xf bound_ctrl:1
	v_cndmask_b32_e64 v47, v108, v107, s[12:13]
	v_mov_b32_dpp v108, v36 row_ror:2 row_mask:0xf bank_mask:0xf bound_ctrl:1
	v_cndmask_b32_e64 v41, v102, v103, s[10:11]
	v_mov_b32_dpp v103, v36 row_ror:1 row_mask:0xf bank_mask:0xf bound_ctrl:1
	v_cndmask_b32_e64 v98, v109, v108, s[12:13]
	v_mov_b32_dpp v109, v37 row_ror:2 row_mask:0xf bank_mask:0xf bound_ctrl:1
	v_cndmask_b32_e64 v48, v103, v104, s[10:11]
	v_mov_b32_dpp v104, v37 row_ror:1 row_mask:0xf bank_mask:0xf bound_ctrl:1
	v_cndmask_b32_e64 v99, v110, v109, s[12:13]
	v_cndmask_b32_e64 v49, v104, v105, s[10:11]
	v_pk_fma_f32 v[98:99], v[92:93], v[98:99], v[96:97]
	v_pk_fma_f32 v[46:47], v[90:91], v[46:47], v[94:95]
	v_pk_fma_f32 v[48:49], v[88:89], v[48:49], v[98:99]
	v_pk_fma_f32 v[40:41], v[86:87], v[40:41], v[46:47]
	v_mul_f32_e32 v46, 0xbfb8aa3b, v26
	v_mul_f32_e32 v47, 0xbfb8aa3b, v27
	v_pk_fma_f32 v[36:37], v[36:37], v[60:61], v[48:49]
	v_mul_f32_e32 v48, 0xbfb8aa3b, v38
	v_mul_f32_e32 v49, 0xbfb8aa3b, v39
	v_exp_f32_e32 v46, v46
	v_exp_f32_e32 v47, v47
	v_exp_f32_e32 v48, v48
	v_exp_f32_e32 v49, v49
	v_add_f32_e32 v46, 1.0, v46
	v_add_f32_e32 v47, 1.0, v47
	v_add_f32_e32 v48, 1.0, v48
	v_add_f32_e32 v49, 1.0, v49
	v_rcp_f32_e32 v46, v46
	v_rcp_f32_e32 v47, v47
	v_rcp_f32_e32 v48, v48
	v_rcp_f32_e32 v49, v49
	v_pk_fma_f32 v[40:41], v[116:117], v[58:59], v[40:41]
	v_pk_mul_f32 v[26:27], v[26:27], v[46:47]
	v_mov_b32_dpp v99, v43 row_ror:2 row_mask:0xf bank_mask:0xf bound_ctrl:1
	v_pk_mul_f32 v[38:39], v[38:39], v[48:49]
	v_mov_b32_dpp v49, v42 row_ror:2 row_mask:0xf bank_mask:0xf bound_ctrl:1
	v_pk_mul_f32 v[26:27], v[26:27], v[40:41]
	v_pk_mul_f32 v[36:37], v[38:39], v[36:37]
	v_mov_b32_dpp v48, v42 row_ror:1 row_mask:0xf bank_mask:0xf bound_ctrl:1
	v_cndmask_b32_e64 v38, v112, v49, s[12:13]
	v_mov_b32_dpp v98, v43 row_ror:1 row_mask:0xf bank_mask:0xf bound_ctrl:1
	v_cndmask_b32_e64 v39, v123, v99, s[12:13]
	v_mov_b32_dpp v110, v44 row_ror:2 row_mask:0xf bank_mask:0xf bound_ctrl:1
	v_mov_b32_dpp v112, v45 row_ror:2 row_mask:0xf bank_mask:0xf bound_ctrl:1
	v_cvt_pk_bf16_f32 v234, v26, v27
	v_cvt_pk_bf16_f32 v235, v36, v37
	v_cndmask_b32_e64 v36, v48, v111, s[10:11]
	v_cndmask_b32_e64 v37, v98, v113, s[10:11]
	v_mov_b32_dpp v105, v44 row_ror:1 row_mask:0xf bank_mask:0xf bound_ctrl:1
	v_cndmask_b32_e64 v46, v125, v110, s[12:13]
	v_mov_b32_dpp v111, v45 row_ror:1 row_mask:0xf bank_mask:0xf bound_ctrl:1
	v_cndmask_b32_e64 v47, v126, v112, s[12:13]
	v_pk_fma_f32 v[38:39], v[70:71], v[38:39], v[82:83]
	v_cndmask_b32_e64 v40, v105, v124, s[10:11]
	v_cndmask_b32_e64 v41, v111, v100, s[10:11]
	v_pk_fma_f32 v[46:47], v[72:73], v[46:47], v[84:85]
	v_pk_fma_f32 v[36:37], v[66:67], v[36:37], v[38:39]
	v_mov_b32_dpp v113, v120 row_ror:2 row_mask:0xf bank_mask:0xf bound_ctrl:1
; __device__ __forceinline__ unsigned cvt_pk_bf16(float lo, float hi) { const f32x2 v = {lo, hi}; unsigned r = __builtin_bit_cast(unsigned, __builtin_convertvector(v, bf16x2_t)); asm volatile("" : "+v"(r)); return r; }
; __device__ __forceinline__ float silu_f(float x) { return x * __builtin_amdgcn_rcpf(1.0f + __expf(-x)); }
; __device__ __forceinline__ float dpp_ror1(float x) { return __builtin_bit_cast(float, __builtin_amdgcn_update_dpp(0, __builtin_bit_cast(int, x), 0x121, 0xf, 0xf, true)); }
; __device__ __forceinline__ float dpp_ror2(float x) { return __builtin_bit_cast(float, __builtin_amdgcn_update_dpp(0, __builtin_bit_cast(int, x), 0x122, 0xf, 0xf, true)); }
;     __device__ __forceinline__ void operator()(const f32x4 (&acc_)[2][2][4][2], const pg8::Unit& u, int wr, int wc, int fr, int fq) const {
;     ...
;                 for (int m = 0; m < 4; ++m) {
;                     f32x4 c[2];
; #pragma unroll
;                     for (int bj = 0; bj < 2; ++bj) {
;                         const f32x4 h0 = acc[ai][bj][m][eh]; f32x4 p1, p2;
; #pragma unroll
;                         for (int e = 0; e < 4; ++e) {
;                             const float r1 = dpp_ror1(h0[e]), r2 = dpp_ror2(h0[e]);
;                             p1[e] = (fr >= 1) ? r1 : pr1[bj][e]; p2[e] = (fr >= 2) ? r2 : pr2[bj][e];
;                             pr1[bj][e] = r1; pr2[bj][e] = r2;
;                         }
;                         c[bj] = bia[bj] + w[bj][0] * p2 + w[bj][1] * p1 + w[bj][2] * h0;
;                     }
;                     f32x4 o;
; #pragma unroll
;                     for (int e = 0; e < 4; ++e) o[e] = silu_f(c[0][e]) * c[1][e];
;                     pk[m].x = cvt_pk_bf16(o[0], o[1]); pk[m].y = cvt_pk_bf16(o[2], o[3]);
;                 }
	v_pk_fma_f32 v[40:41], v[68:69], v[40:41], v[46:47]
	v_pk_fma_f32 v[36:37], v[42:43], v[62:63], v[36:37]
	v_mov_b32_dpp v100, v120 row_ror:1 row_mask:0xf bank_mask:0xf bound_ctrl:1
	v_cndmask_b32_e64 v42, v106, v113, s[12:13]
	v_mov_b32_dpp v106, v121 row_ror:2 row_mask:0xf bank_mask:0xf bound_ctrl:1
	v_pk_fma_f32 v[38:39], v[44:45], v[64:65], v[40:41]
	v_cndmask_b32_e64 v40, v100, v101, s[10:11]
	v_mov_b32_dpp v101, v121 row_ror:1 row_mask:0xf bank_mask:0xf bound_ctrl:1
	v_cndmask_b32_e64 v43, v107, v106, s[12:13]
	v_mov_b32_dpp v107, v118 row_ror:2 row_mask:0xf bank_mask:0xf bound_ctrl:1
	v_cndmask_b32_e64 v41, v101, v102, s[10:11]
	v_mov_b32_dpp v102, v118 row_ror:1 row_mask:0xf bank_mask:0xf bound_ctrl:1
	v_cndmask_b32_e64 v46, v108, v107, s[12:13]
	v_mov_b32_dpp v108, v119 row_ror:2 row_mask:0xf bank_mask:0xf bound_ctrl:1
	v_cndmask_b32_e64 v44, v102, v103, s[10:11]
	v_mov_b32_dpp v103, v119 row_ror:1 row_mask:0xf bank_mask:0xf bound_ctrl:1
	v_cndmask_b32_e64 v47, v109, v108, s[12:13]
	v_pk_fma_f32 v[42:43], v[90:91], v[42:43], v[94:95]
	v_cndmask_b32_e64 v45, v103, v104, s[10:11]
	v_pk_fma_f32 v[46:47], v[92:93], v[46:47], v[96:97]
	v_pk_fma_f32 v[40:41], v[86:87], v[40:41], v[42:43]
	v_mul_f32_e32 v42, 0xbfb8aa3b, v36
	v_pk_fma_f32 v[44:45], v[88:89], v[44:45], v[46:47]
	v_exp_f32_e32 v46, v42
	v_mul_f32_e32 v42, 0xbfb8aa3b, v37
	v_exp_f32_e32 v47, v42
	v_pk_fma_f32 v[42:43], v[118:119], v[60:61], v[44:45]
	v_add_f32_e32 v44, 1.0, v46
	v_mul_f32_e32 v46, 0xbfb8aa3b, v38
	v_add_f32_e32 v45, 1.0, v47
	v_mul_f32_e32 v47, 0xbfb8aa3b, v39
	v_exp_f32_e32 v46, v46
	v_exp_f32_e32 v47, v47
	v_rcp_f32_e32 v44, v44
	v_rcp_f32_e32 v45, v45
	v_add_f32_e32 v46, 1.0, v46
	v_add_f32_e32 v47, 1.0, v47
	v_rcp_f32_e32 v46, v46
	v_rcp_f32_e32 v47, v47
	v_pk_fma_f32 v[40:41], v[120:121], v[58:59], v[40:41]
	v_pk_mul_f32 v[36:37], v[36:37], v[44:45]
	v_mov_b32_dpp v104, v33 row_ror:1 row_mask:0xf bank_mask:0xf bound_ctrl:1
	v_pk_mul_f32 v[38:39], v[38:39], v[46:47]
	v_pk_mul_f32 v[36:37], v[36:37], v[40:41]
	v_pk_mul_f32 v[38:39], v[38:39], v[42:43]
	v_mov_b32_dpp v46, v34 row_ror:1 row_mask:0xf bank_mask:0xf bound_ctrl:1
	v_mov_b32_dpp v47, v34 row_ror:2 row_mask:0xf bank_mask:0xf bound_ctrl:1
	v_cvt_pk_bf16_f32 v238, v36, v37
	v_cvt_pk_bf16_f32 v239, v38, v39
	v_cndmask_b32_e64 v38, v46, v48, s[10:11]
	v_cndmask_b32_e64 v40, v49, v47, s[12:13]
	v_mov_b32_dpp v48, v35 row_ror:1 row_mask:0xf bank_mask:0xf bound_ctrl:1
	v_mov_b32_dpp v49, v35 row_ror:2 row_mask:0xf bank_mask:0xf bound_ctrl:1
	v_cndmask_b32_e64 v39, v48, v98, s[10:11]
	v_cndmask_b32_e64 v41, v99, v49, s[12:13]
	v_mov_b32_dpp v98, v32 row_ror:1 row_mask:0xf bank_mask:0xf bound_ctrl:1
	v_mov_b32_dpp v99, v32 row_ror:2 row_mask:0xf bank_mask:0xf bound_ctrl:1
	v_cndmask_b32_e64 v42, v98, v105, s[10:11]
	v_mov_b32_dpp v105, v33 row_ror:2 row_mask:0xf bank_mask:0xf bound_ctrl:1
	v_pk_fma_f32 v[40:41], v[70:71], v[40:41], v[82:83]
	v_cndmask_b32_e64 v44, v110, v99, s[12:13]
	v_cndmask_b32_e64 v43, v104, v111, s[10:11]
	v_cndmask_b32_e64 v45, v112, v105, s[12:13]
	v_pk_fma_f32 v[38:39], v[66:67], v[38:39], v[40:41]
	v_mov_b32_dpp v109, v28 row_ror:1 row_mask:0xf bank_mask:0xf bound_ctrl:1
	v_mov_b32_dpp v111, v29 row_ror:2 row_mask:0xf bank_mask:0xf bound_ctrl:1
	v_pk_fma_f32 v[44:45], v[72:73], v[44:45], v[84:85]
	v_pk_fma_f32 v[34:35], v[34:35], v[62:63], v[38:39]
	v_cndmask_b32_e64 v38, v109, v100, s[10:11]
	v_mov_b32_dpp v100, v29 row_ror:1 row_mask:0xf bank_mask:0xf bound_ctrl:1
	v_cndmask_b32_e64 v41, v106, v111, s[12:13]
	v_mov_b32_dpp v106, v30 row_ror:2 row_mask:0xf bank_mask:0xf bound_ctrl:1
	v_pk_fma_f32 v[42:43], v[68:69], v[42:43], v[44:45]
	v_cndmask_b32_e64 v39, v100, v101, s[10:11]
	v_mov_b32_dpp v101, v30 row_ror:1 row_mask:0xf bank_mask:0xf bound_ctrl:1
	v_cndmask_b32_e64 v44, v107, v106, s[12:13]
	v_mov_b32_dpp v107, v31 row_ror:2 row_mask:0xf bank_mask:0xf bound_ctrl:1
	v_pk_fma_f32 v[32:33], v[32:33], v[64:65], v[42:43]
	v_mov_b32_dpp v110, v28 row_ror:2 row_mask:0xf bank_mask:0xf bound_ctrl:1
	v_cndmask_b32_e64 v42, v101, v102, s[10:11]
	v_mov_b32_dpp v102, v31 row_ror:1 row_mask:0xf bank_mask:0xf bound_ctrl:1
	v_cndmask_b32_e64 v45, v108, v107, s[12:13]
	v_cndmask_b32_e64 v40, v113, v110, s[12:13]
	v_cndmask_b32_e64 v43, v102, v103, s[10:11]
	v_pk_fma_f32 v[44:45], v[92:93], v[44:45], v[96:97]
	v_pk_fma_f32 v[40:41], v[90:91], v[40:41], v[94:95]
	v_pk_fma_f32 v[42:43], v[88:89], v[42:43], v[44:45]
	v_pk_fma_f32 v[38:39], v[86:87], v[38:39], v[40:41]
	v_mul_f32_e32 v40, 0xbfb8aa3b, v34
	v_mul_f32_e32 v41, 0xbfb8aa3b, v35
	v_pk_fma_f32 v[30:31], v[30:31], v[60:61], v[42:43]
	v_mul_f32_e32 v42, 0xbfb8aa3b, v32
; #define LAS __attribute__((address_space(3)))
; __device__ __forceinline__ unsigned cvt_pk_bf16(float lo, float hi) { const f32x2 v = {lo, hi}; unsigned r = __builtin_bit_cast(unsigned, __builtin_convertvector(v, bf16x2_t)); asm volatile("" : "+v"(r)); return r; }
; __device__ __forceinline__ float silu_f(float x) { return x * __builtin_amdgcn_rcpf(1.0f + __expf(-x)); }
;     __device__ __forceinline__ void operator()(const f32x4 (&acc_)[2][2][4][2], const pg8::Unit& u, int wr, int wc, int fr, int fq) const {
;     ...
;                     const int cc = bj * DFF + ch + 4 * eh;
; #pragma unroll
;                     for (int j = 0; j < 3; ++j) w[bj][j] = *(const LAS f32x4*)(cwl + (2 * j + bj) * 128 + 4 * eh);
;                     bia[bj] = *(const LAS f32x4*)(cwl + (6 + bj) * 128 + 4 * eh);
;                     if (!prompt) { const float* ps = past + (size_t)((blk0 - MP) >> 6) * 2 * DFF2 + cc; hm2[bj] = *(const f32x4*)ps; hm1[bj] = *(const f32x4*)(ps + DFF2); }
;                     else if (ai == 0 && wr == 0) { hm1[bj] = (f32x4){0.f, 0.f, 0.f, 0.f}; hm2[bj] = hm1[bj]; }
;                     else { const int pb = ai * 2 + wr - 1; const LAS float* s = hl + (((pb * 4 + wc) * 2 + 0) * 4 + fq) * 16 + bj * 8 + 4 * eh; hm2[bj] = *(const LAS f32x4*)s; hm1[bj] = *(const LAS f32x4*)(s + 64); }
;     ...
;                 for (int m = 0; m < 4; ++m) {
;                     f32x4 c[2];
; #pragma unroll
;                     for (int bj = 0; bj < 2; ++bj) {
;                         const f32x4 h0 = acc[ai][bj][m][eh]; f32x4 p1, p2;
; #pragma unroll
;                         for (int e = 0; e < 4; ++e) {
;                             const float r1 = dpp_ror1(h0[e]), r2 = dpp_ror2(h0[e]);
;                             p1[e] = (fr >= 1) ? r1 : pr1[bj][e]; p2[e] = (fr >= 2) ? r2 : pr2[bj][e];
;                             pr1[bj][e] = r1; pr2[bj][e] = r2;
;                         }
;                         c[bj] = bia[bj] + w[bj][0] * p2 + w[bj][1] * p1 + w[bj][2] * h0;
;                     }
;                     f32x4 o;
; #pragma unroll
;                     for (int e = 0; e < 4; ++e) o[e] = silu_f(c[0][e]) * c[1][e];
;                     pk[m].x = cvt_pk_bf16(o[0], o[1]); pk[m].y = cvt_pk_bf16(o[2], o[3]);
;                 }
; #pragma unroll
;                 for (int m = 0; m < 4; ++m) *(u32x2*)(act + (size_t)(blk0 + 16 * m + fr) * DFF + ch + 4 * eh) = pk[m];
	v_mul_f32_e32 v43, 0xbfb8aa3b, v33
	v_exp_f32_e32 v40, v40
	v_exp_f32_e32 v41, v41
	v_exp_f32_e32 v42, v42
	v_exp_f32_e32 v43, v43
	v_add_f32_e32 v40, 1.0, v40
	v_add_f32_e32 v41, 1.0, v41
	v_add_f32_e32 v42, 1.0, v42
	v_add_f32_e32 v43, 1.0, v43
	v_rcp_f32_e32 v40, v40
	v_rcp_f32_e32 v41, v41
	v_rcp_f32_e32 v42, v42
	v_rcp_f32_e32 v43, v43
	v_pk_fma_f32 v[28:29], v[28:29], v[58:59], v[38:39]
	v_pk_mul_f32 v[34:35], v[34:35], v[40:41]
	v_mov_b32_dpp v39, v81 row_ror:2 row_mask:0xf bank_mask:0xf bound_ctrl:1
	v_pk_mul_f32 v[32:33], v[32:33], v[42:43]
	v_pk_mul_f32 v[28:29], v[34:35], v[28:29]
	v_pk_mul_f32 v[30:31], v[32:33], v[30:31]
	v_cvt_pk_bf16_f32 v242, v28, v29
	v_cvt_pk_bf16_f32 v243, v30, v31
	v_mov_b32_dpp v31, v78 row_ror:2 row_mask:0xf bank_mask:0xf bound_ctrl:1
	v_mov_b32_dpp v33, v79 row_ror:2 row_mask:0xf bank_mask:0xf bound_ctrl:1
	v_mov_b32_dpp v35, v80 row_ror:2 row_mask:0xf bank_mask:0xf bound_ctrl:1
	v_mov_b32_dpp v30, v78 row_ror:1 row_mask:0xf bank_mask:0xf bound_ctrl:1
	v_cndmask_b32_e64 v32, v47, v31, s[12:13]
	v_mov_b32_dpp v31, v79 row_ror:1 row_mask:0xf bank_mask:0xf bound_ctrl:1
	v_cndmask_b32_e64 v33, v49, v33, s[12:13]
	v_mov_b32_dpp v34, v80 row_ror:1 row_mask:0xf bank_mask:0xf bound_ctrl:1
	v_cndmask_b32_e64 v38, v99, v35, s[12:13]
	v_mov_b32_dpp v35, v81 row_ror:1 row_mask:0xf bank_mask:0xf bound_ctrl:1
	v_cndmask_b32_e64 v39, v105, v39, s[12:13]
	v_cndmask_b32_e64 v30, v30, v46, s[10:11]
	v_cndmask_b32_e64 v31, v31, v48, s[10:11]
	v_cndmask_b32_e64 v34, v34, v98, s[10:11]
	v_cndmask_b32_e64 v35, v35, v104, s[10:11]
	v_pk_fma_f32 v[38:39], v[72:73], v[38:39], v[84:85]
	v_pk_fma_f32 v[32:33], v[70:71], v[32:33], v[82:83]
	v_mov_b32_dpp v41, v76 row_ror:2 row_mask:0xf bank_mask:0xf bound_ctrl:1
	v_pk_fma_f32 v[30:31], v[66:67], v[30:31], v[32:33]
	v_pk_fma_f32 v[32:33], v[68:69], v[34:35], v[38:39]
	v_mov_b32_dpp v35, v74 row_ror:2 row_mask:0xf bank_mask:0xf bound_ctrl:1
	v_mov_b32_dpp v39, v75 row_ror:2 row_mask:0xf bank_mask:0xf bound_ctrl:1
	v_mov_b32_dpp v43, v77 row_ror:2 row_mask:0xf bank_mask:0xf bound_ctrl:1
	v_mov_b32_dpp v34, v74 row_ror:1 row_mask:0xf bank_mask:0xf bound_ctrl:1
	v_cndmask_b32_e64 v38, v110, v35, s[12:13]
	v_mov_b32_dpp v35, v75 row_ror:1 row_mask:0xf bank_mask:0xf bound_ctrl:1
	v_cndmask_b32_e64 v39, v111, v39, s[12:13]
	v_mov_b32_dpp v40, v76 row_ror:1 row_mask:0xf bank_mask:0xf bound_ctrl:1
	v_cndmask_b32_e64 v42, v106, v41, s[12:13]
	v_mov_b32_dpp v41, v77 row_ror:1 row_mask:0xf bank_mask:0xf bound_ctrl:1
	v_cndmask_b32_e64 v43, v107, v43, s[12:13]
	v_pk_fma_f32 v[32:33], v[80:81], v[64:65], v[32:33]
	v_pk_fma_f32 v[30:31], v[78:79], v[62:63], v[30:31]
	v_cndmask_b32_e64 v34, v34, v109, s[10:11]
	v_cndmask_b32_e64 v35, v35, v100, s[10:11]
	v_cndmask_b32_e64 v40, v40, v101, s[10:11]
	v_cndmask_b32_e64 v41, v41, v102, s[10:11]
	v_pk_fma_f32 v[42:43], v[92:93], v[42:43], v[96:97]
	v_pk_fma_f32 v[38:39], v[90:91], v[38:39], v[94:95]
	v_or_b32_e32 v122, s37, v210
	v_pk_fma_f32 v[34:35], v[86:87], v[34:35], v[38:39]
	v_pk_fma_f32 v[38:39], v[88:89], v[40:41], v[42:43]
	v_mul_f32_e32 v40, 0xbfb8aa3b, v30
	v_mul_f32_e32 v41, 0xbfb8aa3b, v31
	v_mul_f32_e32 v42, 0xbfb8aa3b, v32
	v_mul_f32_e32 v43, 0xbfb8aa3b, v33
	v_exp_f32_e32 v40, v40
	v_exp_f32_e32 v41, v41
	v_exp_f32_e32 v42, v42
	v_exp_f32_e32 v43, v43
	v_add_f32_e32 v40, 1.0, v40
	v_add_f32_e32 v41, 1.0, v41
	v_add_f32_e32 v42, 1.0, v42
	v_add_f32_e32 v43, 1.0, v43
	v_rcp_f32_e32 v40, v40
	v_rcp_f32_e32 v41, v41
	v_rcp_f32_e32 v42, v42
	v_rcp_f32_e32 v43, v43
	v_pk_fma_f32 v[38:39], v[76:77], v[60:61], v[38:39]
	v_pk_fma_f32 v[34:35], v[74:75], v[58:59], v[34:35]
	v_pk_mul_f32 v[30:31], v[30:31], v[40:41]
	v_pk_mul_f32 v[32:33], v[32:33], v[42:43]
	v_pk_mul_f32 v[30:31], v[30:31], v[34:35]
	v_pk_mul_f32 v[32:33], v[32:33], v[38:39]
	v_cvt_pk_bf16_f32 v246, v30, v31
	v_cvt_pk_bf16_f32 v247, v32, v33
	v_mad_i64_i32 v[82:83], s[2:3], v122, s22, v[196:197]
	v_or_b32_e32 v26, 16, v122
	v_mad_i64_i32 v[84:85], s[2:3], v26, s22, v[196:197]
	v_or_b32_e32 v26, 32, v122
	v_mad_i64_i32 v[86:87], s[2:3], v26, s22, v[196:197]
	ds_read_b128 v[38:41], v0 offset:16
	ds_read_b128 v[34:37], v0 offset:1040
	ds_read_b128 v[26:29], v0 offset:2064
	ds_read_b128 v[42:45], v0 offset:3088
	v_or_b32_e32 v32, 48, v122
	v_mad_i64_i32 v[88:89], s[2:3], v32, s22, v[196:197]
	s_and_b64 vcc, exec, s[8:9]
	s_mov_b64 s[2:3], -1
	s_cbranch_vccnz .LBB0_1852
	v_add_co_u32_e32 v30, vcc, 0xb000, v114
	s_mov_b64 s[2:3], 0
	s_nop 0
	v_addc_co_u32_e32 v31, vcc, 0, v115, vcc
	global_load_dwordx4 v[74:77], v[114:115], off offset:16
	global_load_dwordx4 v[66:69], v[30:31], off offset:16

; #define LAS __attribute__((address_space(3)))
;     __device__ __forceinline__ void operator()(const f32x4 (&acc_)[2][2][4][2], const pg8::Unit& u, int wr, int wc, int fr, int fq) const {
;     ...
;             for (int eh = 0; eh < 2; ++eh) {
;                 f32x4 w[2][3], bia[2], hm1[2], hm2[2];
; #pragma unroll
;                 for (int bj = 0; bj < 2; ++bj) {
;                     const int cc = bj * DFF + ch + 4 * eh;
; #pragma unroll
;                     for (int j = 0; j < 3; ++j) w[bj][j] = *(const LAS f32x4*)(cwl + (2 * j + bj) * 128 + 4 * eh);
;                     bia[bj] = *(const LAS f32x4*)(cwl + (6 + bj) * 128 + 4 * eh);
;                     if (!prompt) { const float* ps = past + (size_t)((blk0 - MP) >> 6) * 2 * DFF2 + cc; hm2[bj] = *(const f32x4*)ps; hm1[bj] = *(const f32x4*)(ps + DFF2); }
;                     else if (ai == 0 && wr == 0) { hm1[bj] = (f32x4){0.f, 0.f, 0.f, 0.f}; hm2[bj] = hm1[bj]; }
;                     else { const int pb = ai * 2 + wr - 1; const LAS float* s = hl + (((pb * 4 + wc) * 2 + 0) * 4 + fq) * 16 + bj * 8 + 4 * eh; hm2[bj] = *(const LAS f32x4*)s; hm1[bj] = *(const LAS f32x4*)(s + 64); }
;                 }
;                 u32x2 pk[4]; f32x4 pr1[2], pr2[2];
; #pragma unroll
;                 for (int bj = 0; bj < 2; ++bj)
; #pragma unroll
;                     for (int e = 0; e < 4; ++e) { pr1[bj][e] = hm1[bj][e]; pr2[bj][e] = (fr == 0) ? hm2[bj][e] : hm1[bj][e]; }
; #pragma unroll
;                 for (int m = 0; m < 4; ++m) {
;                     f32x4 c[2];
; #pragma unroll
;                     for (int bj = 0; bj < 2; ++bj) {
;                         const f32x4 h0 = acc[ai][bj][m][eh]; f32x4 p1, p2;
; #pragma unroll
;                         for (int e = 0; e < 4; ++e) {
;                             const float r1 = dpp_ror1(h0[e]), r2 = dpp_ror2(h0[e]);
;                             p1[e] = (fr >= 1) ? r1 : pr1[bj][e]; p2[e] = (fr >= 2) ? r2 : pr2[bj][e];
;                             pr1[bj][e] = r1; pr2[bj][e] = r2;
;                         }
;                         c[bj] = bia[bj] + w[bj][0] * p2 + w[bj][1] * p1 + w[bj][2] * h0;
;                     }
;                     f32x4 o;
; #pragma unroll
;                     for (int e = 0; e < 4; ++e) o[e] = silu_f(c[0][e]) * c[1][e];
;                     pk[m].x = cvt_pk_bf16(o[0], o[1]); pk[m].y = cvt_pk_bf16(o[2], o[3]);
;                 }
.LBB0_1858:
	v_mov_b32_e32 v90, v192
	v_mov_b32_e32 v91, v192
	v_mov_b32_e32 v92, v193
	v_mov_b32_e32 v93, v193
	v_mov_b32_e32 v191, v190
	v_mov_b32_e32 v94, v192
	v_mov_b32_e32 v95, v192
	v_pk_mul_f32 v[22:23], v[22:23], v[90:91]
	v_pk_mul_f32 v[24:25], v[24:25], v[94:95]
	v_pk_mul_f32 v[90:91], v[10:11], v[90:91]
	v_mov_b32_e32 v192, v193
	v_pk_mul_f32 v[18:19], v[18:19], v[92:93]
	v_pk_mul_f32 v[92:93], v[6:7], v[92:93]
	v_mov_b32_e32 v6, v190
	v_mov_b32_e32 v7, v190
	v_pk_mul_f32 v[10:11], v[14:15], v[190:191]
	s_waitcnt vmcnt(0) lgkmcnt(4)
	v_cndmask_b32_e64 v0, v66, v74, s[10:11]
	v_cndmask_b32_e64 v15, v67, v75, s[10:11]
	v_cndmask_b32_e64 v74, v69, v77, s[10:11]
	s_waitcnt lgkmcnt(0)
	v_cndmask_b32_e64 v75, v70, v78, s[10:11]
	v_cndmask_b32_e64 v77, v72, v80, s[10:11]
	v_cndmask_b32_e64 v78, v73, v81, s[10:11]
	v_mov_b32_dpp v80, v22 row_ror:2 row_mask:0xf bank_mask:0xf bound_ctrl:1
	v_mov_b32_dpp v81, v23 row_ror:2 row_mask:0xf bank_mask:0xf bound_ctrl:1
	v_pk_mul_f32 v[12:13], v[12:13], v[94:95]
	v_pk_mul_f32 v[94:95], v[8:9], v[192:193]
	v_pk_mul_f32 v[8:9], v[16:17], v[6:7]
	v_cndmask_b32_e64 v17, v68, v76, s[10:11]
	v_cndmask_b32_e64 v76, v71, v79, s[10:11]
	v_mov_b32_dpp v79, v22 row_ror:1 row_mask:0xf bank_mask:0xf bound_ctrl:1
	v_cndmask_b32_e64 v14, v0, v80, s[12:13]
	v_mov_b32_dpp v0, v23 row_ror:1 row_mask:0xf bank_mask:0xf bound_ctrl:1
	v_cndmask_b32_e64 v15, v15, v81, s[12:13]
	v_mov_b32_dpp v96, v24 row_ror:1 row_mask:0xf bank_mask:0xf bound_ctrl:1
	v_mov_b32_dpp v97, v24 row_ror:2 row_mask:0xf bank_mask:0xf bound_ctrl:1
	v_mov_b32_dpp v98, v25 row_ror:2 row_mask:0xf bank_mask:0xf bound_ctrl:1
	v_pk_mul_f32 v[6:7], v[4:5], v[6:7]
	v_pk_mul_f32 v[4:5], v[2:3], v[190:191]
	v_cndmask_b32_e64 v2, v79, v66, s[10:11]
	v_cndmask_b32_e64 v3, v0, v67, s[10:11]
	v_cndmask_b32_e64 v16, v96, v68, s[10:11]
	v_cndmask_b32_e64 v66, v17, v97, s[12:13]
	v_mov_b32_dpp v68, v25 row_ror:1 row_mask:0xf bank_mask:0xf bound_ctrl:1
	v_cndmask_b32_e64 v67, v74, v98, s[12:13]
	v_pk_fma_f32 v[14:15], v[38:39], v[14:15], v[42:43]
	v_cndmask_b32_e64 v17, v68, v69, s[10:11]
	v_pk_fma_f32 v[66:67], v[40:41], v[66:67], v[44:45]
	v_pk_fma_f32 v[2:3], v[34:35], v[2:3], v[14:15]
	v_mov_b32_dpp v74, v90 row_ror:2 row_mask:0xf bank_mask:0xf bound_ctrl:1
	v_pk_fma_f32 v[16:17], v[36:37], v[16:17], v[66:67]
	v_pk_fma_f32 v[2:3], v[22:23], v[26:27], v[2:3]
	v_mov_b32_dpp v69, v90 row_ror:1 row_mask:0xf bank_mask:0xf bound_ctrl:1
	v_cndmask_b32_e64 v22, v75, v74, s[12:13]
	v_mov_b32_dpp v75, v91 row_ror:2 row_mask:0xf bank_mask:0xf bound_ctrl:1
	v_pk_fma_f32 v[14:15], v[24:25], v[28:29], v[16:17]
	v_cndmask_b32_e64 v16, v69, v70, s[10:11]
	v_mov_b32_dpp v70, v91 row_ror:1 row_mask:0xf bank_mask:0xf bound_ctrl:1
	v_cndmask_b32_e64 v23, v76, v75, s[12:13]
	v_mov_b32_dpp v76, v12 row_ror:2 row_mask:0xf bank_mask:0xf bound_ctrl:1
	v_cndmask_b32_e64 v17, v70, v71, s[10:11]
	v_mov_b32_dpp v71, v12 row_ror:1 row_mask:0xf bank_mask:0xf bound_ctrl:1
	v_cndmask_b32_e64 v66, v77, v76, s[12:13]
	v_mov_b32_dpp v77, v13 row_ror:2 row_mask:0xf bank_mask:0xf bound_ctrl:1
	v_cndmask_b32_e64 v24, v71, v72, s[10:11]
	v_mov_b32_dpp v72, v13 row_ror:1 row_mask:0xf bank_mask:0xf bound_ctrl:1
	v_cndmask_b32_e64 v67, v78, v77, s[12:13]
	v_cndmask_b32_e64 v25, v72, v73, s[10:11]
	v_pk_fma_f32 v[66:67], v[60:61], v[66:67], v[64:65]
	v_pk_fma_f32 v[22:23], v[58:59], v[22:23], v[62:63]
	v_pk_fma_f32 v[24:25], v[48:49], v[24:25], v[66:67]
	v_pk_fma_f32 v[16:17], v[46:47], v[16:17], v[22:23]
	v_mul_f32_e32 v22, 0xbfb8aa3b, v2
	v_mul_f32_e32 v23, 0xbfb8aa3b, v3
	v_pk_fma_f32 v[12:13], v[12:13], v[32:33], v[24:25]
	v_mul_f32_e32 v24, 0xbfb8aa3b, v14
	v_mul_f32_e32 v25, 0xbfb8aa3b, v15
	v_exp_f32_e32 v22, v22
	v_exp_f32_e32 v23, v23
	v_exp_f32_e32 v24, v24
	v_exp_f32_e32 v25, v25
	v_add_f32_e32 v22, 1.0, v22
	v_add_f32_e32 v23, 1.0, v23
	v_add_f32_e32 v24, 1.0, v24
	v_add_f32_e32 v25, 1.0, v25
	v_rcp_f32_e32 v22, v22
	v_rcp_f32_e32 v23, v23
	v_rcp_f32_e32 v24, v24
	v_rcp_f32_e32 v25, v25
	v_pk_fma_f32 v[16:17], v[90:91], v[30:31], v[16:17]
	v_pk_mul_f32 v[2:3], v[2:3], v[22:23]
	v_pk_mul_f32 v[20:21], v[20:21], v[192:193]
	v_pk_mul_f32 v[14:15], v[14:15], v[24:25]
	v_pk_mul_f32 v[2:3], v[2:3], v[16:17]
	v_pk_mul_f32 v[12:13], v[14:15], v[12:13]
	v_mov_b32_dpp v24, v18 row_ror:1 row_mask:0xf bank_mask:0xf bound_ctrl:1
	v_mov_b32_dpp v25, v18 row_ror:2 row_mask:0xf bank_mask:0xf bound_ctrl:1
	v_mov_b32_dpp v67, v19 row_ror:2 row_mask:0xf bank_mask:0xf bound_ctrl:1
	v_cvt_pk_bf16_f32 v236, v2, v3
	v_cvt_pk_bf16_f32 v237, v12, v13
	v_cndmask_b32_e64 v12, v24, v79, s[10:11]
	v_cndmask_b32_e64 v14, v80, v25, s[12:13]
	v_mov_b32_dpp v66, v19 row_ror:1 row_mask:0xf bank_mask:0xf bound_ctrl:1
	v_cndmask_b32_e64 v15, v81, v67, s[12:13]
	v_mov_b32_dpp v73, v20 row_ror:2 row_mask:0xf bank_mask:0xf bound_ctrl:1
	v_mov_b32_dpp v79, v21 row_ror:2 row_mask:0xf bank_mask:0xf bound_ctrl:1
	v_cndmask_b32_e64 v13, v66, v0, s[10:11]
	v_mov_b32_dpp v0, v20 row_ror:1 row_mask:0xf bank_mask:0xf bound_ctrl:1
	v_cndmask_b32_e64 v22, v97, v73, s[12:13]
	v_mov_b32_dpp v78, v21 row_ror:1 row_mask:0xf bank_mask:0xf bound_ctrl:1
	v_cndmask_b32_e64 v23, v98, v79, s[12:13]
	v_pk_fma_f32 v[14:15], v[38:39], v[14:15], v[42:43]
	v_cndmask_b32_e64 v16, v0, v96, s[10:11]
	v_cndmask_b32_e64 v17, v78, v68, s[10:11]
	v_pk_fma_f32 v[22:23], v[40:41], v[22:23], v[44:45]
	v_pk_fma_f32 v[12:13], v[34:35], v[12:13], v[14:15]
	v_mov_b32_dpp v80, v92 row_ror:2 row_mask:0xf bank_mask:0xf bound_ctrl:1
	v_pk_fma_f32 v[16:17], v[36:37], v[16:17], v[22:23]
	v_pk_fma_f32 v[12:13], v[18:19], v[26:27], v[12:13]
; __device__ __forceinline__ unsigned cvt_pk_bf16(float lo, float hi) { const f32x2 v = {lo, hi}; unsigned r = __builtin_bit_cast(unsigned, __builtin_convertvector(v, bf16x2_t)); asm volatile("" : "+v"(r)); return r; }
; __device__ __forceinline__ float silu_f(float x) { return x * __builtin_amdgcn_rcpf(1.0f + __expf(-x)); }
; __device__ __forceinline__ float dpp_ror1(float x) { return __builtin_bit_cast(float, __builtin_amdgcn_update_dpp(0, __builtin_bit_cast(int, x), 0x121, 0xf, 0xf, true)); }
; __device__ __forceinline__ float dpp_ror2(float x) { return __builtin_bit_cast(float, __builtin_amdgcn_update_dpp(0, __builtin_bit_cast(int, x), 0x122, 0xf, 0xf, true)); }
;     __device__ __forceinline__ void operator()(const f32x4 (&acc_)[2][2][4][2], const pg8::Unit& u, int wr, int wc, int fr, int fq) const {
;     ...
;                 for (int m = 0; m < 4; ++m) {
;                     f32x4 c[2];
; #pragma unroll
;                     for (int bj = 0; bj < 2; ++bj) {
;                         const f32x4 h0 = acc[ai][bj][m][eh]; f32x4 p1, p2;
; #pragma unroll
;                         for (int e = 0; e < 4; ++e) {
;                             const float r1 = dpp_ror1(h0[e]), r2 = dpp_ror2(h0[e]);
;                             p1[e] = (fr >= 1) ? r1 : pr1[bj][e]; p2[e] = (fr >= 2) ? r2 : pr2[bj][e];
;                             pr1[bj][e] = r1; pr2[bj][e] = r2;
;                         }
;                         c[bj] = bia[bj] + w[bj][0] * p2 + w[bj][1] * p1 + w[bj][2] * h0;
;                     }
;                     f32x4 o;
; #pragma unroll
;                     for (int e = 0; e < 4; ++e) o[e] = silu_f(c[0][e]) * c[1][e];
;                     pk[m].x = cvt_pk_bf16(o[0], o[1]); pk[m].y = cvt_pk_bf16(o[2], o[3]);
;                 }
	v_mov_b32_dpp v68, v92 row_ror:1 row_mask:0xf bank_mask:0xf bound_ctrl:1
	v_cndmask_b32_e64 v18, v74, v80, s[12:13]
	v_mov_b32_dpp v74, v93 row_ror:2 row_mask:0xf bank_mask:0xf bound_ctrl:1
	v_pk_fma_f32 v[14:15], v[20:21], v[28:29], v[16:17]
	v_cndmask_b32_e64 v16, v68, v69, s[10:11]
	v_mov_b32_dpp v69, v93 row_ror:1 row_mask:0xf bank_mask:0xf bound_ctrl:1
	v_cndmask_b32_e64 v19, v75, v74, s[12:13]
	v_mov_b32_dpp v75, v94 row_ror:2 row_mask:0xf bank_mask:0xf bound_ctrl:1
	v_cndmask_b32_e64 v17, v69, v70, s[10:11]
	v_mov_b32_dpp v70, v94 row_ror:1 row_mask:0xf bank_mask:0xf bound_ctrl:1
	v_cndmask_b32_e64 v22, v76, v75, s[12:13]
	v_mov_b32_dpp v76, v95 row_ror:2 row_mask:0xf bank_mask:0xf bound_ctrl:1
	v_cndmask_b32_e64 v20, v70, v71, s[10:11]
	v_mov_b32_dpp v71, v95 row_ror:1 row_mask:0xf bank_mask:0xf bound_ctrl:1
	v_cndmask_b32_e64 v23, v77, v76, s[12:13]
	v_pk_fma_f32 v[18:19], v[58:59], v[18:19], v[62:63]
	v_cndmask_b32_e64 v21, v71, v72, s[10:11]
	v_pk_fma_f32 v[22:23], v[60:61], v[22:23], v[64:65]
	v_pk_fma_f32 v[16:17], v[46:47], v[16:17], v[18:19]
	v_mul_f32_e32 v18, 0xbfb8aa3b, v12
	v_pk_fma_f32 v[20:21], v[48:49], v[20:21], v[22:23]
	v_exp_f32_e32 v22, v18
	v_mul_f32_e32 v18, 0xbfb8aa3b, v13
	v_exp_f32_e32 v23, v18
	v_pk_fma_f32 v[18:19], v[94:95], v[32:33], v[20:21]
	v_add_f32_e32 v20, 1.0, v22
	v_mul_f32_e32 v22, 0xbfb8aa3b, v14
	v_add_f32_e32 v21, 1.0, v23
	v_mul_f32_e32 v23, 0xbfb8aa3b, v15
	v_exp_f32_e32 v22, v22
	v_exp_f32_e32 v23, v23
	v_rcp_f32_e32 v20, v20
	v_rcp_f32_e32 v21, v21
	v_add_f32_e32 v22, 1.0, v22
	v_add_f32_e32 v23, 1.0, v23
	v_rcp_f32_e32 v22, v22
	v_rcp_f32_e32 v23, v23
	v_pk_fma_f32 v[16:17], v[92:93], v[30:31], v[16:17]
	v_pk_mul_f32 v[12:13], v[12:13], v[20:21]
	v_mov_b32_dpp v72, v9 row_ror:2 row_mask:0xf bank_mask:0xf bound_ctrl:1
	v_pk_mul_f32 v[14:15], v[14:15], v[22:23]
	v_pk_mul_f32 v[12:13], v[12:13], v[16:17]
	v_pk_mul_f32 v[14:15], v[14:15], v[18:19]
	v_mov_b32_dpp v22, v10 row_ror:1 row_mask:0xf bank_mask:0xf bound_ctrl:1
	v_mov_b32_dpp v23, v10 row_ror:2 row_mask:0xf bank_mask:0xf bound_ctrl:1
	v_cvt_pk_bf16_f32 v240, v12, v13
	v_cvt_pk_bf16_f32 v241, v14, v15
	v_cndmask_b32_e64 v14, v22, v24, s[10:11]
	v_cndmask_b32_e64 v16, v25, v23, s[12:13]
	v_mov_b32_dpp v24, v11 row_ror:1 row_mask:0xf bank_mask:0xf bound_ctrl:1
	v_mov_b32_dpp v25, v11 row_ror:2 row_mask:0xf bank_mask:0xf bound_ctrl:1
	v_cndmask_b32_e64 v15, v24, v66, s[10:11]
	v_cndmask_b32_e64 v17, v67, v25, s[12:13]
	v_mov_b32_dpp v66, v8 row_ror:1 row_mask:0xf bank_mask:0xf bound_ctrl:1
	v_mov_b32_dpp v67, v8 row_ror:2 row_mask:0xf bank_mask:0xf bound_ctrl:1
	v_cndmask_b32_e64 v18, v66, v0, s[10:11]
	v_mov_b32_dpp v0, v9 row_ror:1 row_mask:0xf bank_mask:0xf bound_ctrl:1
	v_pk_fma_f32 v[16:17], v[38:39], v[16:17], v[42:43]
	v_cndmask_b32_e64 v20, v73, v67, s[12:13]
	v_cndmask_b32_e64 v19, v0, v78, s[10:11]
	v_cndmask_b32_e64 v21, v79, v72, s[12:13]
	v_pk_fma_f32 v[14:15], v[34:35], v[14:15], v[16:17]
	v_mov_b32_dpp v73, v4 row_ror:1 row_mask:0xf bank_mask:0xf bound_ctrl:1
	v_mov_b32_dpp v78, v5 row_ror:2 row_mask:0xf bank_mask:0xf bound_ctrl:1
	v_pk_fma_f32 v[20:21], v[40:41], v[20:21], v[44:45]
	v_pk_fma_f32 v[10:11], v[10:11], v[26:27], v[14:15]
	v_cndmask_b32_e64 v14, v73, v68, s[10:11]
	v_mov_b32_dpp v68, v5 row_ror:1 row_mask:0xf bank_mask:0xf bound_ctrl:1
	v_cndmask_b32_e64 v17, v74, v78, s[12:13]
	v_mov_b32_dpp v74, v6 row_ror:2 row_mask:0xf bank_mask:0xf bound_ctrl:1
	v_pk_fma_f32 v[18:19], v[36:37], v[18:19], v[20:21]
	v_cndmask_b32_e64 v15, v68, v69, s[10:11]
	v_mov_b32_dpp v69, v6 row_ror:1 row_mask:0xf bank_mask:0xf bound_ctrl:1
	v_cndmask_b32_e64 v20, v75, v74, s[12:13]
	v_mov_b32_dpp v75, v7 row_ror:2 row_mask:0xf bank_mask:0xf bound_ctrl:1
	v_pk_fma_f32 v[8:9], v[8:9], v[28:29], v[18:19]
	v_mov_b32_dpp v77, v4 row_ror:2 row_mask:0xf bank_mask:0xf bound_ctrl:1
	v_cndmask_b32_e64 v18, v69, v70, s[10:11]
	v_mov_b32_dpp v70, v7 row_ror:1 row_mask:0xf bank_mask:0xf bound_ctrl:1
	v_cndmask_b32_e64 v21, v76, v75, s[12:13]
	v_cndmask_b32_e64 v16, v80, v77, s[12:13]
	v_cndmask_b32_e64 v19, v70, v71, s[10:11]
	v_pk_fma_f32 v[20:21], v[60:61], v[20:21], v[64:65]
	v_pk_fma_f32 v[16:17], v[58:59], v[16:17], v[62:63]
	v_pk_fma_f32 v[18:19], v[48:49], v[18:19], v[20:21]
	v_pk_fma_f32 v[14:15], v[46:47], v[14:15], v[16:17]
; __device__ __forceinline__ unsigned cvt_pk_bf16(float lo, float hi) { const f32x2 v = {lo, hi}; unsigned r = __builtin_bit_cast(unsigned, __builtin_convertvector(v, bf16x2_t)); asm volatile("" : "+v"(r)); return r; }
; __device__ __forceinline__ float silu_f(float x) { return x * __builtin_amdgcn_rcpf(1.0f + __expf(-x)); }
; #define PG8_BAR __builtin_amdgcn_s_barrier()
; __device__ __forceinline__ float dpp_ror1(float x) { return __builtin_bit_cast(float, __builtin_amdgcn_update_dpp(0, __builtin_bit_cast(int, x), 0x121, 0xf, 0xf, true)); }
; __device__ __forceinline__ float dpp_ror2(float x) { return __builtin_bit_cast(float, __builtin_amdgcn_update_dpp(0, __builtin_bit_cast(int, x), 0x122, 0xf, 0xf, true)); }
;     ...
;         if constexpr (ALIGN_EPI) { if (wr == 1) PG8_BAR; }
;     __device__ __forceinline__ void operator()(const f32x4 (&acc_)[2][2][4][2], const pg8::Unit& u, int wr, int wc, int fr, int fq) const {
;     ...
;                 for (int m = 0; m < 4; ++m) {
;                     f32x4 c[2];
; #pragma unroll
;                     for (int bj = 0; bj < 2; ++bj) {
;                         const f32x4 h0 = acc[ai][bj][m][eh]; f32x4 p1, p2;
; #pragma unroll
;                         for (int e = 0; e < 4; ++e) {
;                             const float r1 = dpp_ror1(h0[e]), r2 = dpp_ror2(h0[e]);
;                             p1[e] = (fr >= 1) ? r1 : pr1[bj][e]; p2[e] = (fr >= 2) ? r2 : pr2[bj][e];
;                             pr1[bj][e] = r1; pr2[bj][e] = r2;
;                         }
;                         c[bj] = bia[bj] + w[bj][0] * p2 + w[bj][1] * p1 + w[bj][2] * h0;
;                     }
;                     f32x4 o;
; #pragma unroll
;                     for (int e = 0; e < 4; ++e) o[e] = silu_f(c[0][e]) * c[1][e];
;                     pk[m].x = cvt_pk_bf16(o[0], o[1]); pk[m].y = cvt_pk_bf16(o[2], o[3]);
;                 }
; #pragma unroll
;                 for (int m = 0; m < 4; ++m) *(u32x2*)(act + (size_t)(blk0 + 16 * m + fr) * DFF + ch + 4 * eh) = pk[m];
	v_mul_f32_e32 v16, 0xbfb8aa3b, v10
	v_mul_f32_e32 v17, 0xbfb8aa3b, v11
	v_pk_fma_f32 v[6:7], v[6:7], v[32:33], v[18:19]
	v_mul_f32_e32 v18, 0xbfb8aa3b, v8
	v_mul_f32_e32 v19, 0xbfb8aa3b, v9
	v_exp_f32_e32 v16, v16
	v_exp_f32_e32 v17, v17
	v_exp_f32_e32 v18, v18
	v_exp_f32_e32 v19, v19
	v_add_f32_e32 v16, 1.0, v16
	v_add_f32_e32 v17, 1.0, v17
	v_add_f32_e32 v18, 1.0, v18
	v_add_f32_e32 v19, 1.0, v19
	v_rcp_f32_e32 v16, v16
	v_rcp_f32_e32 v17, v17
	v_rcp_f32_e32 v18, v18
	v_rcp_f32_e32 v19, v19
	v_pk_fma_f32 v[4:5], v[4:5], v[30:31], v[14:15]
	v_pk_mul_f32 v[10:11], v[10:11], v[16:17]
	v_mov_b32_dpp v15, v57 row_ror:2 row_mask:0xf bank_mask:0xf bound_ctrl:1
	v_pk_mul_f32 v[8:9], v[8:9], v[18:19]
	v_pk_mul_f32 v[4:5], v[10:11], v[4:5]
	v_pk_mul_f32 v[6:7], v[8:9], v[6:7]
	v_mov_b32_dpp v11, v56 row_ror:2 row_mask:0xf bank_mask:0xf bound_ctrl:1
	v_cvt_pk_bf16_f32 v244, v4, v5
	v_cvt_pk_bf16_f32 v245, v6, v7
	v_mov_b32_dpp v7, v54 row_ror:2 row_mask:0xf bank_mask:0xf bound_ctrl:1
	v_mov_b32_dpp v9, v55 row_ror:2 row_mask:0xf bank_mask:0xf bound_ctrl:1
	v_cndmask_b32_e64 v14, v67, v11, s[12:13]
	v_mov_b32_dpp v11, v57 row_ror:1 row_mask:0xf bank_mask:0xf bound_ctrl:1
	v_mov_b32_dpp v6, v54 row_ror:1 row_mask:0xf bank_mask:0xf bound_ctrl:1
	v_cndmask_b32_e64 v8, v23, v7, s[12:13]
	v_mov_b32_dpp v7, v55 row_ror:1 row_mask:0xf bank_mask:0xf bound_ctrl:1
	v_cndmask_b32_e64 v9, v25, v9, s[12:13]
	v_cndmask_b32_e64 v11, v11, v0, s[10:11]
	v_mov_b32_dpp v0, v50 row_ror:1 row_mask:0xf bank_mask:0xf bound_ctrl:1
	v_cndmask_b32_e64 v6, v6, v22, s[10:11]
	v_cndmask_b32_e64 v7, v7, v24, s[10:11]
	v_mov_b32_dpp v17, v50 row_ror:2 row_mask:0xf bank_mask:0xf bound_ctrl:1
	v_cndmask_b32_e64 v16, v0, v73, s[10:11]
	v_mov_b32_dpp v0, v51 row_ror:1 row_mask:0xf bank_mask:0xf bound_ctrl:1
	v_pk_fma_f32 v[8:9], v[38:39], v[8:9], v[42:43]
	v_mov_b32_dpp v10, v56 row_ror:1 row_mask:0xf bank_mask:0xf bound_ctrl:1
	v_cndmask_b32_e64 v15, v72, v15, s[12:13]
	v_cndmask_b32_e64 v18, v77, v17, s[12:13]
	v_mov_b32_dpp v19, v51 row_ror:2 row_mask:0xf bank_mask:0xf bound_ctrl:1
	v_cndmask_b32_e64 v17, v0, v68, s[10:11]
	v_mov_b32_dpp v0, v52 row_ror:1 row_mask:0xf bank_mask:0xf bound_ctrl:1
	v_pk_fma_f32 v[6:7], v[34:35], v[6:7], v[8:9]
	v_cndmask_b32_e64 v10, v10, v66, s[10:11]
	v_cndmask_b32_e64 v19, v78, v19, s[12:13]
	v_mov_b32_dpp v21, v52 row_ror:2 row_mask:0xf bank_mask:0xf bound_ctrl:1
	v_cndmask_b32_e64 v20, v0, v69, s[10:11]
	v_mov_b32_dpp v0, v53 row_ror:1 row_mask:0xf bank_mask:0xf bound_ctrl:1
	v_pk_fma_f32 v[14:15], v[40:41], v[14:15], v[44:45]
	v_pk_fma_f32 v[6:7], v[54:55], v[26:27], v[6:7]
	v_cndmask_b32_e64 v22, v74, v21, s[12:13]
	v_cndmask_b32_e64 v21, v0, v70, s[10:11]
	v_pk_fma_f32 v[8:9], v[36:37], v[10:11], v[14:15]
	v_pk_fma_f32 v[14:15], v[58:59], v[18:19], v[62:63]
	v_mul_f32_e32 v0, 0xbfb8aa3b, v6
	v_pk_fma_f32 v[14:15], v[46:47], v[16:17], v[14:15]
	v_exp_f32_e32 v0, v0
	v_mul_f32_e32 v16, 0xbfb8aa3b, v7
	v_exp_f32_e32 v17, v16
	v_pk_fma_f32 v[8:9], v[56:57], v[28:29], v[8:9]
	v_add_f32_e32 v0, 1.0, v0
	v_rcp_f32_e32 v16, v0
	v_add_f32_e32 v0, 1.0, v17
	v_mul_f32_e32 v17, 0xbfb8aa3b, v8
	v_exp_f32_e32 v18, v17
	v_mul_f32_e32 v17, 0xbfb8aa3b, v9
	v_exp_f32_e32 v19, v17
	v_rcp_f32_e32 v17, v0
	v_add_f32_e32 v0, 1.0, v18
	v_rcp_f32_e32 v18, v0
	v_add_f32_e32 v0, 1.0, v19
	v_mov_b32_dpp v23, v53 row_ror:2 row_mask:0xf bank_mask:0xf bound_ctrl:1
	v_rcp_f32_e32 v19, v0
	v_cndmask_b32_e64 v23, v75, v23, s[12:13]
	v_pk_fma_f32 v[10:11], v[60:61], v[22:23], v[64:65]
	v_pk_fma_f32 v[14:15], v[50:51], v[30:31], v[14:15]
	v_pk_fma_f32 v[10:11], v[48:49], v[20:21], v[10:11]
	v_pk_mul_f32 v[6:7], v[6:7], v[16:17]
	v_pk_fma_f32 v[10:11], v[52:53], v[32:33], v[10:11]
	v_pk_mul_f32 v[8:9], v[8:9], v[18:19]
	v_pk_mul_f32 v[6:7], v[6:7], v[14:15]
	v_pk_mul_f32 v[8:9], v[8:9], v[10:11]
	v_cvt_pk_bf16_f32 v248, v6, v7
	v_cvt_pk_bf16_f32 v249, v8, v9
	s_andn2_b64 vcc, exec, s[6:7]
	s_mov_b64 s[2:3], -1
	global_store_dwordx4 v[82:83], v[234:237], off
	global_store_dwordx4 v[84:85], v[238:241], off
	global_store_dwordx4 v[86:87], v[242:245], off
	global_store_dwordx4 v[88:89], v[246:249], off
	s_cbranch_vccnz .LBB0_1769
	s_andn2_b64 vcc, exec, s[0:1]
	s_cbranch_vccnz .LBB0_1768
	s_barrier
	s_branch .LBB0_1768
